# forget-gate tile: dead denormal-rescue code of __logf removed for all 128 elements (bit-exact)
# speedup vs baseline: 1.0060x; 1.0017x over previous
.LBB0_288:
	s_andn2_b64 vcc, exec, s[34:35]
	s_cbranch_vccnz .LBB0_290
	v_mul_f32_e32 v128, 0xbfb8aa3b, v182
	v_exp_f32_e32 v128, v128
	v_mul_f32_e32 v161, 0x3fb8aa3b, v203
	v_exp_f32_e32 v161, v161
	v_add_f32_e32 v128, 1.0, v128
	v_rcp_f32_e32 v157, v128
	v_mul_f32_e32 v128, 0x3fb8aa3b, v182
	v_exp_f32_e32 v128, v128
	v_add_f32_e32 v161, 1.0, v161
	v_rcp_f32_e32 v211, v161
	v_mul_f32_e32 v161, 0x3fb8aa3b, v181
	v_add_f32_e32 v128, 1.0, v128
	v_rcp_f32_e32 v206, v128
	v_mul_f32_e32 v128, 0xbfb8aa3b, v183
	v_exp_f32_e32 v128, v128
	v_exp_f32_e32 v161, v161
	v_add_f32_e32 v128, 1.0, v128
	v_rcp_f32_e32 v159, v128
	v_mul_f32_e32 v128, 0x3fb8aa3b, v183
	v_exp_f32_e32 v128, v128
	v_add_f32_e32 v161, 1.0, v161
	v_rcp_f32_e32 v215, v161
	v_add_f32_e32 v128, 1.0, v128
	v_rcp_f32_e32 v207, v128
	global_load_dwordx4 v[128:131], v[148:149], off offset:16
	global_load_dwordx4 v[132:135], v[148:149], off
	s_waitcnt vmcnt(1)
	v_pk_add_f32 v[222:223], v[128:129], 1.0 op_sel_hi:[1,0] neg_lo:[1,0] neg_hi:[1,0]
	s_waitcnt vmcnt(0)
	v_pk_add_f32 v[208:209], v[132:133], 1.0 op_sel_hi:[1,0] neg_lo:[1,0] neg_hi:[1,0]
	v_pk_add_f32 v[212:213], v[134:135], 1.0 op_sel_hi:[1,0] neg_lo:[1,0] neg_hi:[1,0]
	v_fma_f32 v132, v157, v208, v132
	v_max_f32_e32 v132, 0xda24260, v132
	v_fma_f32 v133, v159, v209, v133
	v_max_f32_e32 v133, 0xda24260, v133
	v_log_f32_e32 v132, v132
	v_mul_f32_e32 v159, 0x3fb8aa3b, v202
	v_exp_f32_e32 v159, v159
	v_pk_add_f32 v[230:231], v[130:131], 1.0 op_sel_hi:[1,0] neg_lo:[1,0] neg_hi:[1,0]
	v_mul_f32_e32 v157, 0x3f317217, v132
	v_fma_f32 v157, v132, s95, -v157
	v_fmac_f32_e32 v157, 0x3377d1cf, v132
	v_fmac_f32_e32 v157, 0x3f317217, v132
	v_cmp_lt_f32_e64 s[42:43], |v132|, s62
	v_add_f32_e32 v159, 1.0, v159
	v_rcp_f32_e32 v210, v159
	v_cndmask_b32_e64 v132, v132, v157, s[42:43]
	v_mul_f32_e32 v159, 0xbfb8aa3b, v203
	v_log_f32_e32 v133, v133
	v_exp_f32_e32 v159, v159
	v_pk_mul_f32 v[208:209], v[206:207], v[208:209]
	v_pk_mul_f32 v[206:207], v[210:211], v[212:213]
	v_mul_f32_e32 v157, 0x3f317217, v133
	v_fma_f32 v157, v133, s95, -v157
	v_fmac_f32_e32 v157, 0x3377d1cf, v133
	v_fmac_f32_e32 v157, 0x3f317217, v133
	v_cmp_lt_f32_e64 s[42:43], |v133|, s62
	v_add_f32_e32 v159, 1.0, v159
	v_rcp_f32_e32 v159, v159
	v_cndmask_b32_e64 v133, v133, v157, s[42:43]
	v_mul_f32_e32 v157, 0xbfb8aa3b, v202
	v_exp_f32_e32 v157, v157
	v_fmac_f32_e32 v135, v159, v213
	v_max_f32_e32 v135, 0xda24260, v135
	v_mul_f32_e32 v159, 0x3fb8aa3b, v180
	v_add_f32_e32 v157, 1.0, v157
	v_rcp_f32_e32 v157, v157
	v_exp_f32_e32 v159, v159
	v_lshl_add_u64 v[210:211], v[146:147], 0, v[178:179]
	v_fma_f32 v134, v157, v212, v134
	v_max_f32_e32 v134, 0xda24260, v134
	v_add_f32_e32 v159, 1.0, v159
	v_rcp_f32_e32 v214, v159
	v_log_f32_e32 v134, v134
	v_mul_f32_e32 v159, 0xbfb8aa3b, v181
	v_exp_f32_e32 v159, v159
	v_mul_f32_e32 v157, 0x3f317217, v134
	v_fma_f32 v157, v134, s95, -v157
	v_fmac_f32_e32 v157, 0x3377d1cf, v134
	v_fmac_f32_e32 v157, 0x3f317217, v134
	v_cmp_lt_f32_e64 s[42:43], |v134|, s62
	v_add_f32_e32 v159, 1.0, v159
	v_rcp_f32_e32 v159, v159
	v_cndmask_b32_e64 v134, v134, v157, s[42:43]
	s_nop 0
	v_log_f32_e32 v135, v135
	s_nop 0
	v_mul_f32_e32 v157, 0x3f317217, v135
	v_fma_f32 v157, v135, s95, -v157
	v_fmac_f32_e32 v157, 0x3377d1cf, v135
	v_fmac_f32_e32 v157, 0x3f317217, v135
	v_cmp_lt_f32_e64 s[42:43], |v135|, s62
	s_nop 1
	v_cndmask_b32_e64 v135, v135, v157, s[42:43]
	v_mul_f32_e32 v157, 0xbfb8aa3b, v180
	v_exp_f32_e32 v157, v157
	s_nop 0
	v_add_f32_e32 v157, 1.0, v157
	v_rcp_f32_e32 v157, v157
	s_nop 0
	v_fma_f32 v128, v157, v222, v128
	v_max_f32_e32 v128, 0xda24260, v128
	s_nop 1
	v_log_f32_e32 v128, v128
	s_nop 0
	v_mul_f32_e32 v157, 0x3f317217, v128
	v_fma_f32 v157, v128, s95, -v157
	v_fmac_f32_e32 v157, 0x3377d1cf, v128
	v_fmac_f32_e32 v157, 0x3f317217, v128
	v_cmp_lt_f32_e64 s[42:43], |v128|, s62
	s_nop 1
	v_cndmask_b32_e64 v128, v128, v157, s[42:43]
	v_mov_b32_e32 v218, v128
	v_fma_f32 v128, v159, v223, v129
	v_max_f32_e32 v128, 0xda24260, v128
	s_nop 1
	v_log_f32_e32 v128, v128
	s_nop 0
	v_mul_f32_e32 v129, 0x3f317217, v128
	v_fma_f32 v129, v128, s95, -v129
	v_fmac_f32_e32 v129, 0x3377d1cf, v128
	v_fmac_f32_e32 v129, 0x3f317217, v128
	v_cmp_lt_f32_e64 s[42:43], |v128|, s62
	s_nop 1
	v_cndmask_b32_e64 v128, v128, v129, s[42:43]
	v_mov_b32_e32 v219, v128
	v_mul_f32_e32 v128, 0xbfb8aa3b, v204
	v_exp_f32_e32 v128, v128
	v_mul_f32_e32 v129, 0xbfb8aa3b, v205
	v_exp_f32_e32 v129, v129
	v_add_f32_e32 v128, 1.0, v128
	v_rcp_f32_e32 v157, v128
	v_add_f32_e32 v129, 1.0, v129
	v_rcp_f32_e32 v159, v129
	v_mul_f32_e32 v128, 0x3fb8aa3b, v204
	v_fma_f32 v130, v157, v230, v130
	v_max_f32_e32 v130, 0xda24260, v130
	v_fmac_f32_e32 v131, v159, v231
	v_mul_f32_e32 v129, 0x3fb8aa3b, v205
	v_log_f32_e32 v130, v130
	v_exp_f32_e32 v128, v128
	v_exp_f32_e32 v129, v129
	v_mul_f32_e32 v157, 0x3f317217, v130
	v_fma_f32 v157, v130, s95, -v157
	v_fmac_f32_e32 v157, 0x3377d1cf, v130
	v_fmac_f32_e32 v157, 0x3f317217, v130
	v_cmp_lt_f32_e64 s[42:43], |v130|, s62
	v_add_f32_e32 v128, 1.0, v128
	v_add_f32_e32 v129, 1.0, v129
	v_cndmask_b32_e64 v130, v130, v157, s[42:43]
	v_mov_b32_e32 v220, v130
	v_max_f32_e32 v130, 0xda24260, v131
	v_rcp_f32_e32 v128, v128
	v_rcp_f32_e32 v129, v129
	v_log_f32_e32 v130, v130
	v_pk_mul_f32 v[128:129], v[128:129], v[230:231]
	v_mul_f32_e32 v131, 0x3f317217, v130
	v_fma_f32 v131, v130, s95, -v131
	v_fmac_f32_e32 v131, 0x3377d1cf, v130
	v_fmac_f32_e32 v131, 0x3f317217, v130
	v_cmp_lt_f32_e64 s[42:43], |v130|, s62
	s_nop 1
	v_cndmask_b32_e64 v130, v130, v131, s[42:43]
	v_mov_b32_e32 v221, v130
	v_pk_mul_f32 v[130:131], v[214:215], v[222:223]
	global_store_dwordx4 v[210:211], v[132:135], off
	global_store_dwordx4 v[210:211], v[218:221], off offset:16

.LBB0_300:
	s_andn2_b64 vcc, exec, s[36:37]
	s_cbranch_vccnz .LBB0_302
	global_load_dwordx4 v[120:123], v[148:149], off offset:528
	global_load_dwordx4 v[124:127], v[148:149], off offset:512
	v_mul_f32_e32 v157, 0xbfb8aa3b, v132
	v_exp_f32_e32 v157, v157
	v_mul_f32_e32 v159, 0x3fb8aa3b, v132
	v_exp_f32_e32 v159, v159
	v_mul_f32_e32 v161, 0x3fb8aa3b, v133
	v_add_f32_e32 v157, 1.0, v157
	v_rcp_f32_e32 v157, v157
	v_add_f32_e32 v159, 1.0, v159
	v_rcp_f32_e32 v182, v159
	v_mul_f32_e32 v159, 0xbfb8aa3b, v133
	v_exp_f32_e32 v159, v159
	v_exp_f32_e32 v161, v161
	v_lshl_add_u64 v[178:179], v[150:151], 0, v[178:179]
	v_add_f32_e32 v159, 1.0, v159
	v_rcp_f32_e32 v159, v159
	v_add_f32_e32 v161, 1.0, v161
	v_rcp_f32_e32 v183, v161
	v_mul_f32_e32 v161, 0x3fb8aa3b, v135
	v_exp_f32_e32 v161, v161
	s_waitcnt vmcnt(1)
	v_pk_add_f32 v[214:215], v[120:121], 1.0 op_sel_hi:[1,0] neg_lo:[1,0] neg_hi:[1,0]
	s_waitcnt vmcnt(0)
	v_pk_add_f32 v[202:203], v[124:125], 1.0 op_sel_hi:[1,0] neg_lo:[1,0] neg_hi:[1,0]
	v_pk_add_f32 v[206:207], v[126:127], 1.0 op_sel_hi:[1,0] neg_lo:[1,0] neg_hi:[1,0]
	v_fma_f32 v124, v157, v202, v124
	v_max_f32_e32 v124, 0xda24260, v124
	v_fma_f32 v125, v159, v203, v125
	v_max_f32_e32 v125, 0xda24260, v125
	v_log_f32_e32 v124, v124
	v_mul_f32_e32 v159, 0x3fb8aa3b, v134
	v_exp_f32_e32 v159, v159
	v_pk_add_f32 v[218:219], v[122:123], 1.0 op_sel_hi:[1,0] neg_lo:[1,0] neg_hi:[1,0]
	v_mul_f32_e32 v157, 0x3f317217, v124
	v_fma_f32 v157, v124, s95, -v157
	v_fmac_f32_e32 v157, 0x3377d1cf, v124
	v_fmac_f32_e32 v157, 0x3f317217, v124
	v_cmp_lt_f32_e64 s[46:47], |v124|, s62
	v_add_f32_e32 v159, 1.0, v159
	v_rcp_f32_e32 v204, v159
	v_cndmask_b32_e64 v124, v124, v157, s[46:47]
	v_mul_f32_e32 v159, 0xbfb8aa3b, v135
	v_log_f32_e32 v125, v125
	v_exp_f32_e32 v159, v159
	v_add_f32_e32 v161, 1.0, v161
	v_rcp_f32_e32 v205, v161
	v_mul_f32_e32 v157, 0x3f317217, v125
	v_fma_f32 v157, v125, s95, -v157
	v_fmac_f32_e32 v157, 0x3377d1cf, v125
	v_fmac_f32_e32 v157, 0x3f317217, v125
	v_cmp_lt_f32_e64 s[46:47], |v125|, s62
	v_add_f32_e32 v159, 1.0, v159
	v_rcp_f32_e32 v159, v159
	v_cndmask_b32_e64 v125, v125, v157, s[46:47]
	v_mul_f32_e32 v157, 0xbfb8aa3b, v134
	v_exp_f32_e32 v157, v157
	v_fmac_f32_e32 v127, v159, v207
	v_max_f32_e32 v127, 0xda24260, v127
	v_mul_f32_e32 v159, 0x3fb8aa3b, v130
	v_add_f32_e32 v157, 1.0, v157
	v_rcp_f32_e32 v157, v157
	v_exp_f32_e32 v159, v159
	v_mul_f32_e32 v161, 0x3fb8aa3b, v131
	v_exp_f32_e32 v161, v161
	v_fma_f32 v126, v157, v206, v126
	v_max_f32_e32 v126, 0xda24260, v126
	v_add_f32_e32 v159, 1.0, v159
	v_rcp_f32_e32 v208, v159
	v_log_f32_e32 v126, v126
	v_mul_f32_e32 v159, 0xbfb8aa3b, v131
	v_exp_f32_e32 v159, v159
	v_add_f32_e32 v161, 1.0, v161
	v_mul_f32_e32 v157, 0x3f317217, v126
	v_fma_f32 v157, v126, s95, -v157
	v_fmac_f32_e32 v157, 0x3377d1cf, v126
	v_fmac_f32_e32 v157, 0x3f317217, v126
	v_cmp_lt_f32_e64 s[46:47], |v126|, s62
	v_add_f32_e32 v159, 1.0, v159
	v_rcp_f32_e32 v159, v159
	v_cndmask_b32_e64 v126, v126, v157, s[46:47]
	v_rcp_f32_e32 v209, v161
	v_log_f32_e32 v127, v127
	v_pk_mul_f32 v[202:203], v[182:183], v[202:203]
	v_pk_mul_f32 v[182:183], v[204:205], v[206:207]
	v_mul_f32_e32 v157, 0x3f317217, v127
	v_fma_f32 v157, v127, s95, -v157
	v_fmac_f32_e32 v157, 0x3377d1cf, v127
	v_fmac_f32_e32 v157, 0x3f317217, v127
	v_cmp_lt_f32_e64 s[46:47], |v127|, s62
	s_nop 1
	v_cndmask_b32_e64 v127, v127, v157, s[46:47]
	v_mul_f32_e32 v157, 0xbfb8aa3b, v130
	v_exp_f32_e32 v157, v157
	s_nop 0
	v_add_f32_e32 v157, 1.0, v157
	v_rcp_f32_e32 v157, v157
	s_nop 0
	v_fma_f32 v120, v157, v214, v120
	v_max_f32_e32 v120, 0xda24260, v120
	s_nop 1
	v_log_f32_e32 v120, v120
	s_nop 0
	v_mul_f32_e32 v157, 0x3f317217, v120
	v_fma_f32 v157, v120, s95, -v157
	v_fmac_f32_e32 v157, 0x3377d1cf, v120
	v_fmac_f32_e32 v157, 0x3f317217, v120
	v_cmp_lt_f32_e64 s[46:47], |v120|, s62
	s_nop 1
	v_cndmask_b32_e64 v120, v120, v157, s[46:47]
	v_mov_b32_e32 v210, v120
	v_fma_f32 v120, v159, v215, v121
	v_max_f32_e32 v120, 0xda24260, v120
	s_nop 1
	v_log_f32_e32 v120, v120
	s_nop 0
	v_mul_f32_e32 v121, 0x3f317217, v120
	v_fma_f32 v121, v120, s95, -v121
	v_fmac_f32_e32 v121, 0x3377d1cf, v120
	v_fmac_f32_e32 v121, 0x3f317217, v120
	v_cmp_lt_f32_e64 s[46:47], |v120|, s62
	s_nop 1
	v_cndmask_b32_e64 v120, v120, v121, s[46:47]
	v_mov_b32_e32 v211, v120
	v_mul_f32_e32 v120, 0xbfb8aa3b, v180
	v_exp_f32_e32 v120, v120
	v_mul_f32_e32 v121, 0xbfb8aa3b, v181
	v_exp_f32_e32 v121, v121
	v_add_f32_e32 v120, 1.0, v120
	v_rcp_f32_e32 v157, v120
	v_add_f32_e32 v121, 1.0, v121
	v_rcp_f32_e32 v159, v121
	v_mul_f32_e32 v120, 0x3fb8aa3b, v180
	v_fma_f32 v122, v157, v218, v122
	v_max_f32_e32 v122, 0xda24260, v122
	v_fmac_f32_e32 v123, v159, v219
	v_mul_f32_e32 v121, 0x3fb8aa3b, v181
	v_log_f32_e32 v122, v122
	v_exp_f32_e32 v120, v120
	v_exp_f32_e32 v121, v121
	v_mul_f32_e32 v157, 0x3f317217, v122
	v_fma_f32 v157, v122, s95, -v157
	v_fmac_f32_e32 v157, 0x3377d1cf, v122
	v_fmac_f32_e32 v157, 0x3f317217, v122
	v_cmp_lt_f32_e64 s[46:47], |v122|, s62
	v_add_f32_e32 v120, 1.0, v120
	v_add_f32_e32 v121, 1.0, v121
	v_cndmask_b32_e64 v122, v122, v157, s[46:47]
	v_mov_b32_e32 v212, v122
	v_max_f32_e32 v122, 0xda24260, v123
	v_rcp_f32_e32 v120, v120
	v_rcp_f32_e32 v121, v121
	v_log_f32_e32 v122, v122
	v_pk_mul_f32 v[120:121], v[120:121], v[218:219]
	v_mul_f32_e32 v123, 0x3f317217, v122
	v_fma_f32 v123, v122, s95, -v123
	v_fmac_f32_e32 v123, 0x3377d1cf, v122
	v_fmac_f32_e32 v123, 0x3f317217, v122
	v_cmp_lt_f32_e64 s[46:47], |v122|, s62
	s_nop 1
	v_cndmask_b32_e64 v122, v122, v123, s[46:47]
	v_mov_b32_e32 v213, v122
	v_pk_mul_f32 v[122:123], v[208:209], v[214:215]
	global_store_dwordx4 v[178:179], v[124:127], off
	global_store_dwordx4 v[178:179], v[210:213], off offset:16

.LBB0_312:
	s_andn2_b64 vcc, exec, s[36:37]
	s_cbranch_vccnz .LBB0_314
	v_mul_f32_e32 v120, 0xbfb8aa3b, v134
	v_exp_f32_e32 v120, v120
	v_mul_f32_e32 v159, 0x3fb8aa3b, v179
	v_exp_f32_e32 v159, v159
	v_add_f32_e32 v120, 1.0, v120
	v_rcp_f32_e32 v131, v120
	v_mul_f32_e32 v120, 0x3fb8aa3b, v134
	v_exp_f32_e32 v120, v120
	v_add_f32_e32 v159, 1.0, v159
	v_rcp_f32_e32 v205, v159
	v_mul_f32_e32 v159, 0x3fb8aa3b, v133
	v_add_f32_e32 v120, 1.0, v120
	v_rcp_f32_e32 v182, v120
	v_mul_f32_e32 v120, 0xbfb8aa3b, v135
	v_exp_f32_e32 v120, v120
	v_exp_f32_e32 v159, v159
	v_add_f32_e32 v120, 1.0, v120
	v_rcp_f32_e32 v157, v120
	v_mul_f32_e32 v120, 0x3fb8aa3b, v135
	v_exp_f32_e32 v120, v120
	v_add_f32_e32 v159, 1.0, v159
	v_rcp_f32_e32 v209, v159
	v_add_f32_e32 v120, 1.0, v120
	v_rcp_f32_e32 v183, v120
	global_load_dwordx4 v[120:123], v[148:149], off offset:16
	global_load_dwordx4 v[124:127], v[148:149], off
	s_waitcnt vmcnt(1)
	v_pk_add_f32 v[214:215], v[120:121], 1.0 op_sel_hi:[1,0] neg_lo:[1,0] neg_hi:[1,0]
	s_waitcnt vmcnt(0)
	v_pk_add_f32 v[202:203], v[124:125], 1.0 op_sel_hi:[1,0] neg_lo:[1,0] neg_hi:[1,0]
	v_pk_add_f32 v[206:207], v[126:127], 1.0 op_sel_hi:[1,0] neg_lo:[1,0] neg_hi:[1,0]
	v_fma_f32 v124, v131, v202, v124
	v_max_f32_e32 v124, 0xda24260, v124
	v_fma_f32 v125, v157, v203, v125
	v_max_f32_e32 v125, 0xda24260, v125
	v_log_f32_e32 v124, v124
	v_mul_f32_e32 v157, 0x3fb8aa3b, v178
	v_exp_f32_e32 v157, v157
	v_pk_add_f32 v[218:219], v[122:123], 1.0 op_sel_hi:[1,0] neg_lo:[1,0] neg_hi:[1,0]
	v_mul_f32_e32 v131, 0x3f317217, v124
	v_fma_f32 v131, v124, s95, -v131
	v_fmac_f32_e32 v131, 0x3377d1cf, v124
	v_fmac_f32_e32 v131, 0x3f317217, v124
	v_cmp_lt_f32_e64 s[46:47], |v124|, s62
	v_add_f32_e32 v157, 1.0, v157
	v_rcp_f32_e32 v204, v157
	v_cndmask_b32_e64 v124, v124, v131, s[46:47]
	v_mul_f32_e32 v157, 0xbfb8aa3b, v179
	v_log_f32_e32 v125, v125
	v_exp_f32_e32 v157, v157
	v_pk_mul_f32 v[202:203], v[182:183], v[202:203]
	v_pk_mul_f32 v[182:183], v[204:205], v[206:207]
	v_mul_f32_e32 v131, 0x3f317217, v125
	v_fma_f32 v131, v125, s95, -v131
	v_fmac_f32_e32 v131, 0x3377d1cf, v125
	v_fmac_f32_e32 v131, 0x3f317217, v125
	v_cmp_lt_f32_e64 s[46:47], |v125|, s62
	v_add_f32_e32 v157, 1.0, v157
	v_rcp_f32_e32 v157, v157
	v_cndmask_b32_e64 v125, v125, v131, s[46:47]
	v_mul_f32_e32 v131, 0xbfb8aa3b, v178
	v_exp_f32_e32 v131, v131
	v_fmac_f32_e32 v127, v157, v207
	v_max_f32_e32 v127, 0xda24260, v127
	v_mul_f32_e32 v157, 0x3fb8aa3b, v132
	v_add_f32_e32 v131, 1.0, v131
	v_rcp_f32_e32 v131, v131
	v_exp_f32_e32 v157, v157
	v_lshl_add_u64 v[204:205], v[146:147], 0, v[128:129]
	v_fma_f32 v126, v131, v206, v126
	v_max_f32_e32 v126, 0xda24260, v126
	v_add_f32_e32 v157, 1.0, v157
	v_rcp_f32_e32 v208, v157
	v_log_f32_e32 v126, v126
	v_mul_f32_e32 v157, 0xbfb8aa3b, v133
	v_exp_f32_e32 v157, v157
	v_mul_f32_e32 v131, 0x3f317217, v126
	v_fma_f32 v131, v126, s95, -v131
	v_fmac_f32_e32 v131, 0x3377d1cf, v126
	v_fmac_f32_e32 v131, 0x3f317217, v126
	v_cmp_lt_f32_e64 s[46:47], |v126|, s62
	v_add_f32_e32 v157, 1.0, v157
	v_rcp_f32_e32 v157, v157
	v_cndmask_b32_e64 v126, v126, v131, s[46:47]
	s_nop 0
	v_log_f32_e32 v127, v127
	s_nop 0
	v_mul_f32_e32 v131, 0x3f317217, v127
	v_fma_f32 v131, v127, s95, -v131
	v_fmac_f32_e32 v131, 0x3377d1cf, v127
	v_fmac_f32_e32 v131, 0x3f317217, v127
	v_cmp_lt_f32_e64 s[46:47], |v127|, s62
	s_nop 1
	v_cndmask_b32_e64 v127, v127, v131, s[46:47]
	v_mul_f32_e32 v131, 0xbfb8aa3b, v132
	v_exp_f32_e32 v131, v131
	s_nop 0
	v_add_f32_e32 v131, 1.0, v131
	v_rcp_f32_e32 v131, v131
	s_nop 0
	v_fma_f32 v120, v131, v214, v120
	v_max_f32_e32 v120, 0xda24260, v120
	s_nop 1
	v_log_f32_e32 v120, v120
	s_nop 0
	v_mul_f32_e32 v131, 0x3f317217, v120
	v_fma_f32 v131, v120, s95, -v131
	v_fmac_f32_e32 v131, 0x3377d1cf, v120
	v_fmac_f32_e32 v131, 0x3f317217, v120
	v_cmp_lt_f32_e64 s[46:47], |v120|, s62
	s_nop 1
	v_cndmask_b32_e64 v120, v120, v131, s[46:47]
	v_mov_b32_e32 v210, v120
	v_fma_f32 v120, v157, v215, v121
	v_max_f32_e32 v120, 0xda24260, v120
	s_nop 1
	v_log_f32_e32 v120, v120
	s_nop 0
	v_mul_f32_e32 v121, 0x3f317217, v120
	v_fma_f32 v121, v120, s95, -v121
	v_fmac_f32_e32 v121, 0x3377d1cf, v120
	v_fmac_f32_e32 v121, 0x3f317217, v120
	v_cmp_lt_f32_e64 s[46:47], |v120|, s62
	s_nop 1
	v_cndmask_b32_e64 v120, v120, v121, s[46:47]
	v_mov_b32_e32 v211, v120
	v_mul_f32_e32 v120, 0xbfb8aa3b, v180
	v_exp_f32_e32 v120, v120
	v_mul_f32_e32 v121, 0xbfb8aa3b, v181
	v_exp_f32_e32 v121, v121
	v_add_f32_e32 v120, 1.0, v120
	v_rcp_f32_e32 v131, v120
	v_add_f32_e32 v121, 1.0, v121
	v_rcp_f32_e32 v157, v121
	v_mul_f32_e32 v120, 0x3fb8aa3b, v180
	v_fma_f32 v122, v131, v218, v122
	v_max_f32_e32 v122, 0xda24260, v122
	v_fmac_f32_e32 v123, v157, v219
	v_mul_f32_e32 v121, 0x3fb8aa3b, v181
	v_log_f32_e32 v122, v122
	v_exp_f32_e32 v120, v120
	v_exp_f32_e32 v121, v121
	v_mul_f32_e32 v131, 0x3f317217, v122
	v_fma_f32 v131, v122, s95, -v131
	v_fmac_f32_e32 v131, 0x3377d1cf, v122
	v_fmac_f32_e32 v131, 0x3f317217, v122
	v_cmp_lt_f32_e64 s[46:47], |v122|, s62
	v_add_f32_e32 v120, 1.0, v120
	v_add_f32_e32 v121, 1.0, v121
	v_cndmask_b32_e64 v122, v122, v131, s[46:47]
	v_mov_b32_e32 v212, v122
	v_max_f32_e32 v122, 0xda24260, v123
	v_rcp_f32_e32 v120, v120
	v_rcp_f32_e32 v121, v121
	v_log_f32_e32 v122, v122
	v_pk_mul_f32 v[120:121], v[120:121], v[218:219]
	v_mul_f32_e32 v123, 0x3f317217, v122
	v_fma_f32 v123, v122, s95, -v123
	v_fmac_f32_e32 v123, 0x3377d1cf, v122
	v_fmac_f32_e32 v123, 0x3f317217, v122
	v_cmp_lt_f32_e64 s[46:47], |v122|, s62
	s_nop 1
	v_cndmask_b32_e64 v122, v122, v123, s[46:47]
	v_mov_b32_e32 v213, v122
	v_pk_mul_f32 v[122:123], v[208:209], v[214:215]
	global_store_dwordx4 v[204:205], v[124:127], off
	global_store_dwordx4 v[204:205], v[210:213], off offset:16

.LBB0_324:
	s_andn2_b64 vcc, exec, s[36:37]
	s_cbranch_vccnz .LBB0_326
	global_load_dwordx4 v[112:115], v[148:149], off offset:528
	global_load_dwordx4 v[116:119], v[148:149], off offset:512
	v_mul_f32_e32 v132, 0xbfb8aa3b, v124
	v_exp_f32_e32 v132, v132
	v_mul_f32_e32 v133, 0xbfb8aa3b, v125
	v_exp_f32_e32 v133, v133
	v_mul_f32_e32 v161, 0x3fb8aa3b, v127
	v_add_f32_e32 v132, 1.0, v132
	v_rcp_f32_e32 v157, v132
	v_add_f32_e32 v133, 1.0, v133
	v_rcp_f32_e32 v159, v133
	v_exp_f32_e32 v161, v161
	v_mul_f32_e32 v132, 0x3fb8aa3b, v124
	v_mul_f32_e32 v133, 0x3fb8aa3b, v125
	v_exp_f32_e32 v132, v132
	v_add_f32_e32 v161, 1.0, v161
	v_rcp_f32_e32 v179, v161
	v_mul_f32_e32 v161, 0x3fb8aa3b, v123
	v_exp_f32_e32 v133, v133
	v_exp_f32_e32 v161, v161
	v_add_f32_e32 v132, 1.0, v132
	v_rcp_f32_e32 v132, v132
	v_add_f32_e32 v133, 1.0, v133
	v_add_f32_e32 v161, 1.0, v161
	v_rcp_f32_e32 v133, v133
	v_rcp_f32_e32 v183, v161
	v_lshl_add_u64 v[128:129], v[150:151], 0, v[128:129]
	s_waitcnt vmcnt(1)
	v_pk_add_f32 v[206:207], v[112:113], 1.0 op_sel_hi:[1,0] neg_lo:[1,0] neg_hi:[1,0]
	s_waitcnt vmcnt(0)
	v_pk_add_f32 v[134:135], v[116:117], 1.0 op_sel_hi:[1,0] neg_lo:[1,0] neg_hi:[1,0]
	v_pk_add_f32 v[180:181], v[118:119], 1.0 op_sel_hi:[1,0] neg_lo:[1,0] neg_hi:[1,0]
	v_fma_f32 v116, v157, v134, v116
	v_max_f32_e32 v116, 0xda24260, v116
	v_fma_f32 v117, v159, v135, v117
	v_max_f32_e32 v117, 0xda24260, v117
	v_log_f32_e32 v116, v116
	v_mul_f32_e32 v159, 0x3fb8aa3b, v126
	v_exp_f32_e32 v159, v159
	v_pk_add_f32 v[208:209], v[114:115], 1.0 op_sel_hi:[1,0] neg_lo:[1,0] neg_hi:[1,0]
	v_mul_f32_e32 v157, 0x3f317217, v116
	v_fma_f32 v157, v116, s95, -v157
	v_fmac_f32_e32 v157, 0x3377d1cf, v116
	v_fmac_f32_e32 v157, 0x3f317217, v116
	v_cmp_lt_f32_e64 s[46:47], |v116|, s62
	v_add_f32_e32 v159, 1.0, v159
	v_rcp_f32_e32 v178, v159
	v_cndmask_b32_e64 v116, v116, v157, s[46:47]
	v_mul_f32_e32 v159, 0xbfb8aa3b, v127
	v_log_f32_e32 v117, v117
	v_exp_f32_e32 v159, v159
	v_pk_mul_f32 v[134:135], v[132:133], v[134:135]
	v_pk_mul_f32 v[132:133], v[178:179], v[180:181]
	v_mul_f32_e32 v157, 0x3f317217, v117
	v_fma_f32 v157, v117, s95, -v157
	v_fmac_f32_e32 v157, 0x3377d1cf, v117
	v_fmac_f32_e32 v157, 0x3f317217, v117
	v_cmp_lt_f32_e64 s[46:47], |v117|, s62
	v_add_f32_e32 v159, 1.0, v159
	v_rcp_f32_e32 v159, v159
	v_cndmask_b32_e64 v117, v117, v157, s[46:47]
	v_mul_f32_e32 v157, 0xbfb8aa3b, v126
	v_exp_f32_e32 v157, v157
	v_fmac_f32_e32 v119, v159, v181
	v_max_f32_e32 v119, 0xda24260, v119
	v_mul_f32_e32 v159, 0x3fb8aa3b, v122
	v_add_f32_e32 v157, 1.0, v157
	v_rcp_f32_e32 v157, v157
	v_exp_f32_e32 v159, v159
	v_fma_f32 v118, v157, v180, v118
	v_max_f32_e32 v118, 0xda24260, v118
	v_add_f32_e32 v159, 1.0, v159
	v_rcp_f32_e32 v182, v159
	v_log_f32_e32 v118, v118
	v_mul_f32_e32 v159, 0xbfb8aa3b, v123
	v_exp_f32_e32 v159, v159
	v_mul_f32_e32 v157, 0x3f317217, v118
	v_fma_f32 v157, v118, s95, -v157
	v_fmac_f32_e32 v157, 0x3377d1cf, v118
	v_fmac_f32_e32 v157, 0x3f317217, v118
	v_cmp_lt_f32_e64 s[46:47], |v118|, s62
	v_add_f32_e32 v159, 1.0, v159
	v_rcp_f32_e32 v159, v159
	v_cndmask_b32_e64 v118, v118, v157, s[46:47]
	s_nop 0
	v_log_f32_e32 v119, v119
	s_nop 0
	v_mul_f32_e32 v157, 0x3f317217, v119
	v_fma_f32 v157, v119, s95, -v157
	v_fmac_f32_e32 v157, 0x3377d1cf, v119
	v_fmac_f32_e32 v157, 0x3f317217, v119
	v_cmp_lt_f32_e64 s[46:47], |v119|, s62
	s_nop 1
	v_cndmask_b32_e64 v119, v119, v157, s[46:47]
	v_mul_f32_e32 v157, 0xbfb8aa3b, v122
	v_exp_f32_e32 v157, v157
	s_nop 0
	v_add_f32_e32 v157, 1.0, v157
	v_rcp_f32_e32 v157, v157
	s_nop 0
	v_fma_f32 v112, v157, v206, v112
	v_max_f32_e32 v112, 0xda24260, v112
	s_nop 1
	v_log_f32_e32 v112, v112
	s_nop 0
	v_mul_f32_e32 v157, 0x3f317217, v112
	v_fma_f32 v157, v112, s95, -v157
	v_fmac_f32_e32 v157, 0x3377d1cf, v112
	v_fmac_f32_e32 v157, 0x3f317217, v112
	v_cmp_lt_f32_e64 s[46:47], |v112|, s62
	s_nop 1
	v_cndmask_b32_e64 v112, v112, v157, s[46:47]
	v_mov_b32_e32 v202, v112
	v_fma_f32 v112, v159, v207, v113
	v_max_f32_e32 v112, 0xda24260, v112
	s_nop 1
	v_log_f32_e32 v112, v112
	s_nop 0
	v_mul_f32_e32 v113, 0x3f317217, v112
	v_fma_f32 v113, v112, s95, -v113
	v_fmac_f32_e32 v113, 0x3377d1cf, v112
	v_fmac_f32_e32 v113, 0x3f317217, v112
	v_cmp_lt_f32_e64 s[46:47], |v112|, s62
	s_nop 1
	v_cndmask_b32_e64 v112, v112, v113, s[46:47]
	v_mov_b32_e32 v203, v112
	v_mul_f32_e32 v112, 0xbfb8aa3b, v130
	v_exp_f32_e32 v112, v112
	v_mul_f32_e32 v113, 0xbfb8aa3b, v131
	v_exp_f32_e32 v113, v113
	v_add_f32_e32 v112, 1.0, v112
	v_rcp_f32_e32 v157, v112
	v_add_f32_e32 v113, 1.0, v113
	v_rcp_f32_e32 v159, v113
	v_mul_f32_e32 v112, 0x3fb8aa3b, v130
	v_fma_f32 v114, v157, v208, v114
	v_max_f32_e32 v114, 0xda24260, v114
	v_fmac_f32_e32 v115, v159, v209
	v_mul_f32_e32 v113, 0x3fb8aa3b, v131
	v_log_f32_e32 v114, v114
	v_exp_f32_e32 v112, v112
	v_exp_f32_e32 v113, v113
	v_mul_f32_e32 v157, 0x3f317217, v114
	v_fma_f32 v157, v114, s95, -v157
	v_fmac_f32_e32 v157, 0x3377d1cf, v114
	v_fmac_f32_e32 v157, 0x3f317217, v114
	v_cmp_lt_f32_e64 s[46:47], |v114|, s62
	v_add_f32_e32 v112, 1.0, v112
	v_add_f32_e32 v113, 1.0, v113
	v_cndmask_b32_e64 v114, v114, v157, s[46:47]
	v_mov_b32_e32 v204, v114
	v_max_f32_e32 v114, 0xda24260, v115
	v_rcp_f32_e32 v112, v112
	v_rcp_f32_e32 v113, v113
	v_log_f32_e32 v114, v114
	v_pk_mul_f32 v[112:113], v[112:113], v[208:209]
	v_mul_f32_e32 v115, 0x3f317217, v114
	v_fma_f32 v115, v114, s95, -v115
	v_fmac_f32_e32 v115, 0x3377d1cf, v114
	v_fmac_f32_e32 v115, 0x3f317217, v114
	v_cmp_lt_f32_e64 s[46:47], |v114|, s62
	s_nop 1
	v_cndmask_b32_e64 v114, v114, v115, s[46:47]
	v_mov_b32_e32 v205, v114
	v_pk_mul_f32 v[114:115], v[182:183], v[206:207]
	global_store_dwordx4 v[128:129], v[116:119], off
	global_store_dwordx4 v[128:129], v[202:205], off offset:16

.LBB0_336:
	s_andn2_b64 vcc, exec, s[36:37]
	s_cbranch_vccnz .LBB0_338
	v_mul_f32_e32 v112, 0xbfb8aa3b, v126
	v_exp_f32_e32 v112, v112
	v_mul_f32_e32 v159, 0x3fb8aa3b, v129
	v_exp_f32_e32 v159, v159
	v_add_f32_e32 v112, 1.0, v112
	v_rcp_f32_e32 v123, v112
	v_mul_f32_e32 v112, 0x3fb8aa3b, v126
	v_exp_f32_e32 v112, v112
	v_add_f32_e32 v159, 1.0, v159
	v_rcp_f32_e32 v179, v159
	v_mul_f32_e32 v159, 0x3fb8aa3b, v125
	v_add_f32_e32 v112, 1.0, v112
	v_rcp_f32_e32 v132, v112
	v_mul_f32_e32 v112, 0xbfb8aa3b, v127
	v_exp_f32_e32 v112, v112
	v_exp_f32_e32 v159, v159
	v_add_f32_e32 v112, 1.0, v112
	v_rcp_f32_e32 v157, v112
	v_mul_f32_e32 v112, 0x3fb8aa3b, v127
	v_exp_f32_e32 v112, v112
	v_add_f32_e32 v159, 1.0, v159
	v_rcp_f32_e32 v183, v159
	v_add_f32_e32 v112, 1.0, v112
	v_rcp_f32_e32 v133, v112
	global_load_dwordx4 v[112:115], v[148:149], off offset:16
	global_load_dwordx4 v[116:119], v[148:149], off
	s_waitcnt vmcnt(1)
	v_pk_add_f32 v[206:207], v[112:113], 1.0 op_sel_hi:[1,0] neg_lo:[1,0] neg_hi:[1,0]
	s_waitcnt vmcnt(0)
	v_pk_add_f32 v[134:135], v[116:117], 1.0 op_sel_hi:[1,0] neg_lo:[1,0] neg_hi:[1,0]
	v_pk_add_f32 v[180:181], v[118:119], 1.0 op_sel_hi:[1,0] neg_lo:[1,0] neg_hi:[1,0]
	v_fma_f32 v116, v123, v134, v116
	v_max_f32_e32 v116, 0xda24260, v116
	v_fma_f32 v117, v157, v135, v117
	v_max_f32_e32 v117, 0xda24260, v117
	v_log_f32_e32 v116, v116
	v_mul_f32_e32 v157, 0x3fb8aa3b, v128
	v_exp_f32_e32 v157, v157
	v_pk_add_f32 v[208:209], v[114:115], 1.0 op_sel_hi:[1,0] neg_lo:[1,0] neg_hi:[1,0]
	v_mul_f32_e32 v123, 0x3f317217, v116
	v_fma_f32 v123, v116, s95, -v123
	v_fmac_f32_e32 v123, 0x3377d1cf, v116
	v_fmac_f32_e32 v123, 0x3f317217, v116
	v_cmp_lt_f32_e64 s[46:47], |v116|, s62
	v_add_f32_e32 v157, 1.0, v157
	v_rcp_f32_e32 v178, v157
	v_cndmask_b32_e64 v116, v116, v123, s[46:47]
	v_mul_f32_e32 v157, 0xbfb8aa3b, v129
	v_log_f32_e32 v117, v117
	v_exp_f32_e32 v157, v157
	v_pk_mul_f32 v[134:135], v[132:133], v[134:135]
	v_pk_mul_f32 v[132:133], v[178:179], v[180:181]
	v_mul_f32_e32 v123, 0x3f317217, v117
	v_fma_f32 v123, v117, s95, -v123
	v_fmac_f32_e32 v123, 0x3377d1cf, v117
	v_fmac_f32_e32 v123, 0x3f317217, v117
	v_cmp_lt_f32_e64 s[46:47], |v117|, s62
	v_add_f32_e32 v157, 1.0, v157
	v_rcp_f32_e32 v157, v157
	v_cndmask_b32_e64 v117, v117, v123, s[46:47]
	v_mul_f32_e32 v123, 0xbfb8aa3b, v128
	v_exp_f32_e32 v123, v123
	v_fmac_f32_e32 v119, v157, v181
	v_max_f32_e32 v119, 0xda24260, v119
	v_mul_f32_e32 v157, 0x3fb8aa3b, v124
	v_add_f32_e32 v123, 1.0, v123
	v_rcp_f32_e32 v123, v123
	v_exp_f32_e32 v157, v157
	v_lshl_add_u64 v[178:179], v[146:147], 0, v[120:121]
	v_fma_f32 v118, v123, v180, v118
	v_max_f32_e32 v118, 0xda24260, v118
	v_add_f32_e32 v157, 1.0, v157
	v_rcp_f32_e32 v182, v157
	v_log_f32_e32 v118, v118
	v_mul_f32_e32 v157, 0xbfb8aa3b, v125
	v_exp_f32_e32 v157, v157
	v_mul_f32_e32 v123, 0x3f317217, v118
	v_fma_f32 v123, v118, s95, -v123
	v_fmac_f32_e32 v123, 0x3377d1cf, v118
	v_fmac_f32_e32 v123, 0x3f317217, v118
	v_cmp_lt_f32_e64 s[46:47], |v118|, s62
	v_add_f32_e32 v157, 1.0, v157
	v_rcp_f32_e32 v157, v157
	v_cndmask_b32_e64 v118, v118, v123, s[46:47]
	s_nop 0
	v_log_f32_e32 v119, v119
	s_nop 0
	v_mul_f32_e32 v123, 0x3f317217, v119
	v_fma_f32 v123, v119, s95, -v123
	v_fmac_f32_e32 v123, 0x3377d1cf, v119
	v_fmac_f32_e32 v123, 0x3f317217, v119
	v_cmp_lt_f32_e64 s[46:47], |v119|, s62
	s_nop 1
	v_cndmask_b32_e64 v119, v119, v123, s[46:47]
	v_mul_f32_e32 v123, 0xbfb8aa3b, v124
	v_exp_f32_e32 v123, v123
	s_nop 0
	v_add_f32_e32 v123, 1.0, v123
	v_rcp_f32_e32 v123, v123
	s_nop 0
	v_fma_f32 v112, v123, v206, v112
	v_max_f32_e32 v112, 0xda24260, v112
	s_nop 1
	v_log_f32_e32 v112, v112
	s_nop 0
	v_mul_f32_e32 v123, 0x3f317217, v112
	v_fma_f32 v123, v112, s95, -v123
	v_fmac_f32_e32 v123, 0x3377d1cf, v112
	v_fmac_f32_e32 v123, 0x3f317217, v112
	v_cmp_lt_f32_e64 s[46:47], |v112|, s62
	s_nop 1
	v_cndmask_b32_e64 v112, v112, v123, s[46:47]
	v_mov_b32_e32 v202, v112
	v_fma_f32 v112, v157, v207, v113
	v_max_f32_e32 v112, 0xda24260, v112
	s_nop 1
	v_log_f32_e32 v112, v112
	s_nop 0
	v_mul_f32_e32 v113, 0x3f317217, v112
	v_fma_f32 v113, v112, s95, -v113
	v_fmac_f32_e32 v113, 0x3377d1cf, v112
	v_fmac_f32_e32 v113, 0x3f317217, v112
	v_cmp_lt_f32_e64 s[46:47], |v112|, s62
	s_nop 1
	v_cndmask_b32_e64 v112, v112, v113, s[46:47]
	v_mov_b32_e32 v203, v112
	v_mul_f32_e32 v112, 0xbfb8aa3b, v130
	v_exp_f32_e32 v112, v112
	v_mul_f32_e32 v113, 0xbfb8aa3b, v131
	v_exp_f32_e32 v113, v113
	v_add_f32_e32 v112, 1.0, v112
	v_rcp_f32_e32 v123, v112
	v_add_f32_e32 v113, 1.0, v113
	v_rcp_f32_e32 v157, v113
	v_mul_f32_e32 v112, 0x3fb8aa3b, v130
	v_fma_f32 v114, v123, v208, v114
	v_max_f32_e32 v114, 0xda24260, v114
	v_fmac_f32_e32 v115, v157, v209
	v_mul_f32_e32 v113, 0x3fb8aa3b, v131
	v_log_f32_e32 v114, v114
	v_exp_f32_e32 v112, v112
	v_exp_f32_e32 v113, v113
	v_mul_f32_e32 v123, 0x3f317217, v114
	v_fma_f32 v123, v114, s95, -v123
	v_fmac_f32_e32 v123, 0x3377d1cf, v114
	v_fmac_f32_e32 v123, 0x3f317217, v114
	v_cmp_lt_f32_e64 s[46:47], |v114|, s62
	v_add_f32_e32 v112, 1.0, v112
	v_add_f32_e32 v113, 1.0, v113
	v_cndmask_b32_e64 v114, v114, v123, s[46:47]
	v_mov_b32_e32 v204, v114
	v_max_f32_e32 v114, 0xda24260, v115
	v_rcp_f32_e32 v112, v112
	v_rcp_f32_e32 v113, v113
	v_log_f32_e32 v114, v114
	v_pk_mul_f32 v[112:113], v[112:113], v[208:209]
	v_mul_f32_e32 v115, 0x3f317217, v114
	v_fma_f32 v115, v114, s95, -v115
	v_fmac_f32_e32 v115, 0x3377d1cf, v114
	v_fmac_f32_e32 v115, 0x3f317217, v114
	v_cmp_lt_f32_e64 s[46:47], |v114|, s62
	s_nop 1
	v_cndmask_b32_e64 v114, v114, v115, s[46:47]
	v_mov_b32_e32 v205, v114
	v_pk_mul_f32 v[114:115], v[182:183], v[206:207]
	global_store_dwordx4 v[178:179], v[116:119], off
	global_store_dwordx4 v[178:179], v[202:205], off offset:16

.LBB0_348:
	s_andn2_b64 vcc, exec, s[36:37]
	s_cbranch_vccnz .LBB0_350
	global_load_dwordx4 v[104:107], v[148:149], off offset:528
	global_load_dwordx4 v[108:111], v[148:149], off offset:512
	v_mul_f32_e32 v124, 0xbfb8aa3b, v116
	v_exp_f32_e32 v124, v124
	v_mul_f32_e32 v125, 0xbfb8aa3b, v117
	v_exp_f32_e32 v125, v125
	v_lshl_add_u64 v[120:121], v[150:151], 0, v[120:121]
	v_add_f32_e32 v124, 1.0, v124
	v_rcp_f32_e32 v128, v124
	v_add_f32_e32 v125, 1.0, v125
	v_rcp_f32_e32 v129, v125
	v_mul_f32_e32 v124, 0x3fb8aa3b, v116
	v_mul_f32_e32 v125, 0x3fb8aa3b, v117
	v_exp_f32_e32 v124, v124
	v_exp_f32_e32 v125, v125
	v_add_f32_e32 v124, 1.0, v124
	v_add_f32_e32 v125, 1.0, v125
	v_rcp_f32_e32 v124, v124
	v_rcp_f32_e32 v125, v125
	s_waitcnt vmcnt(1)
	v_pk_add_f32 v[134:135], v[104:105], 1.0 op_sel_hi:[1,0] neg_lo:[1,0] neg_hi:[1,0]
	s_waitcnt vmcnt(0)
	v_pk_add_f32 v[126:127], v[108:109], 1.0 op_sel_hi:[1,0] neg_lo:[1,0] neg_hi:[1,0]
	v_pk_add_f32 v[130:131], v[110:111], 1.0 op_sel_hi:[1,0] neg_lo:[1,0] neg_hi:[1,0]
	v_fma_f32 v108, v128, v126, v108
	v_max_f32_e32 v108, 0xda24260, v108
	v_fma_f32 v109, v129, v127, v109
	v_max_f32_e32 v109, 0xda24260, v109
	v_log_f32_e32 v108, v108
	v_mul_f32_e32 v129, 0xbfb8aa3b, v119
	v_exp_f32_e32 v129, v129
	v_pk_add_f32 v[182:183], v[106:107], 1.0 op_sel_hi:[1,0] neg_lo:[1,0] neg_hi:[1,0]
	v_mul_f32_e32 v128, 0x3f317217, v108
	v_fma_f32 v128, v108, s95, -v128
	v_fmac_f32_e32 v128, 0x3377d1cf, v108
	v_fmac_f32_e32 v128, 0x3f317217, v108
	v_cmp_lt_f32_e64 s[46:47], |v108|, s62
	v_add_f32_e32 v129, 1.0, v129
	v_rcp_f32_e32 v133, v129
	v_cndmask_b32_e64 v108, v108, v128, s[46:47]
	v_fmac_f32_e32 v111, v133, v131
	v_log_f32_e32 v109, v109
	v_max_f32_e32 v111, 0xda24260, v111
	v_mul_f32_e32 v133, 0xbfb8aa3b, v115
	v_exp_f32_e32 v133, v133
	v_mul_f32_e32 v128, 0x3f317217, v109
	v_fma_f32 v128, v109, s95, -v128
	v_fmac_f32_e32 v128, 0x3377d1cf, v109
	v_fmac_f32_e32 v128, 0x3f317217, v109
	v_cmp_lt_f32_e64 s[46:47], |v109|, s62
	v_add_f32_e32 v133, 1.0, v133
	v_rcp_f32_e32 v159, v133
	v_cndmask_b32_e64 v109, v109, v128, s[46:47]
	v_mul_f32_e32 v128, 0xbfb8aa3b, v118
	v_exp_f32_e32 v128, v128
	v_mul_f32_e32 v129, 0x3fb8aa3b, v119
	v_mul_f32_e32 v133, 0x3fb8aa3b, v115
	v_exp_f32_e32 v129, v129
	v_add_f32_e32 v128, 1.0, v128
	v_rcp_f32_e32 v132, v128
	v_mul_f32_e32 v128, 0x3fb8aa3b, v118
	v_exp_f32_e32 v128, v128
	v_exp_f32_e32 v133, v133
	v_fma_f32 v110, v132, v130, v110
	v_max_f32_e32 v110, 0xda24260, v110
	v_add_f32_e32 v128, 1.0, v128
	v_add_f32_e32 v129, 1.0, v129
	v_log_f32_e32 v110, v110
	v_add_f32_e32 v133, 1.0, v133
	v_rcp_f32_e32 v128, v128
	v_rcp_f32_e32 v129, v129
	v_mul_f32_e32 v132, 0x3f317217, v110
	v_fma_f32 v132, v110, s95, -v132
	v_fmac_f32_e32 v132, 0x3377d1cf, v110
	v_fmac_f32_e32 v132, 0x3f317217, v110
	v_cmp_lt_f32_e64 s[46:47], |v110|, s62
	v_rcp_f32_e32 v133, v133
	v_pk_mul_f32 v[126:127], v[124:125], v[126:127]
	v_cndmask_b32_e64 v110, v110, v132, s[46:47]
	v_pk_mul_f32 v[124:125], v[128:129], v[130:131]
	v_log_f32_e32 v111, v111
	s_nop 0
	v_mul_f32_e32 v132, 0x3f317217, v111
	v_fma_f32 v132, v111, s95, -v132
	v_fmac_f32_e32 v132, 0x3377d1cf, v111
	v_fmac_f32_e32 v132, 0x3f317217, v111
	v_cmp_lt_f32_e64 s[46:47], |v111|, s62
	s_nop 1
	v_cndmask_b32_e64 v111, v111, v132, s[46:47]
	v_mul_f32_e32 v132, 0xbfb8aa3b, v114
	v_exp_f32_e32 v132, v132
	s_nop 0
	v_add_f32_e32 v132, 1.0, v132
	v_rcp_f32_e32 v157, v132
	v_mul_f32_e32 v132, 0x3fb8aa3b, v114
	v_exp_f32_e32 v132, v132
	v_fma_f32 v104, v157, v134, v104
	v_max_f32_e32 v104, 0xda24260, v104
	v_add_f32_e32 v132, 1.0, v132
	v_rcp_f32_e32 v132, v132
	v_log_f32_e32 v104, v104
	s_nop 0
	v_mul_f32_e32 v157, 0x3f317217, v104
	v_fma_f32 v157, v104, s95, -v157
	v_fmac_f32_e32 v157, 0x3377d1cf, v104
	v_fmac_f32_e32 v157, 0x3f317217, v104
	v_cmp_lt_f32_e64 s[46:47], |v104|, s62
	s_nop 1
	v_cndmask_b32_e64 v104, v104, v157, s[46:47]
	v_mov_b32_e32 v178, v104
	v_fma_f32 v104, v159, v135, v105
	v_max_f32_e32 v104, 0xda24260, v104
	s_nop 1
	v_log_f32_e32 v104, v104
	s_nop 0
	v_mul_f32_e32 v105, 0x3f317217, v104
	v_fma_f32 v105, v104, s95, -v105
	v_fmac_f32_e32 v105, 0x3377d1cf, v104
	v_fmac_f32_e32 v105, 0x3f317217, v104
	v_cmp_lt_f32_e64 s[46:47], |v104|, s62
	s_nop 1
	v_cndmask_b32_e64 v104, v104, v105, s[46:47]
	v_mov_b32_e32 v179, v104
	v_mul_f32_e32 v104, 0xbfb8aa3b, v122
	v_exp_f32_e32 v104, v104
	v_mul_f32_e32 v105, 0xbfb8aa3b, v123
	v_exp_f32_e32 v105, v105
	v_add_f32_e32 v104, 1.0, v104
	v_rcp_f32_e32 v157, v104
	v_add_f32_e32 v105, 1.0, v105
	v_rcp_f32_e32 v159, v105
	v_mul_f32_e32 v104, 0x3fb8aa3b, v122
	v_fma_f32 v106, v157, v182, v106
	v_max_f32_e32 v106, 0xda24260, v106
	v_fmac_f32_e32 v107, v159, v183
	v_mul_f32_e32 v105, 0x3fb8aa3b, v123
	v_log_f32_e32 v106, v106
	v_exp_f32_e32 v104, v104
	v_exp_f32_e32 v105, v105
	v_mul_f32_e32 v157, 0x3f317217, v106
	v_fma_f32 v157, v106, s95, -v157
	v_fmac_f32_e32 v157, 0x3377d1cf, v106
	v_fmac_f32_e32 v157, 0x3f317217, v106
	v_cmp_lt_f32_e64 s[46:47], |v106|, s62
	v_add_f32_e32 v104, 1.0, v104
	v_add_f32_e32 v105, 1.0, v105
	v_cndmask_b32_e64 v106, v106, v157, s[46:47]
	v_mov_b32_e32 v180, v106
	v_max_f32_e32 v106, 0xda24260, v107
	v_rcp_f32_e32 v104, v104
	v_rcp_f32_e32 v105, v105
	v_log_f32_e32 v106, v106
	v_pk_mul_f32 v[104:105], v[104:105], v[182:183]
	v_mul_f32_e32 v107, 0x3f317217, v106
	v_fma_f32 v107, v106, s95, -v107
	v_fmac_f32_e32 v107, 0x3377d1cf, v106
	v_fmac_f32_e32 v107, 0x3f317217, v106
	v_cmp_lt_f32_e64 s[46:47], |v106|, s62
	s_nop 1
	v_cndmask_b32_e64 v106, v106, v107, s[46:47]
	v_mov_b32_e32 v181, v106
	v_pk_mul_f32 v[106:107], v[132:133], v[134:135]
	global_store_dwordx4 v[120:121], v[108:111], off
	global_store_dwordx4 v[120:121], v[178:181], off offset:16

.LBB0_360:
	s_andn2_b64 vcc, exec, s[36:37]
	s_cbranch_vccnz .LBB0_362
	v_mul_f32_e32 v104, 0xbfb8aa3b, v118
	v_exp_f32_e32 v104, v104
	v_mul_f32_e32 v129, 0xbfb8aa3b, v121
	v_exp_f32_e32 v129, v129
	v_mul_f32_e32 v133, 0xbfb8aa3b, v117
	v_add_f32_e32 v104, 1.0, v104
	v_rcp_f32_e32 v115, v104
	v_mul_f32_e32 v104, 0x3fb8aa3b, v118
	v_exp_f32_e32 v104, v104
	v_add_f32_e32 v129, 1.0, v129
	v_rcp_f32_e32 v132, v129
	v_exp_f32_e32 v133, v133
	v_add_f32_e32 v104, 1.0, v104
	v_rcp_f32_e32 v124, v104
	v_mul_f32_e32 v104, 0xbfb8aa3b, v119
	v_exp_f32_e32 v104, v104
	v_add_f32_e32 v133, 1.0, v133
	v_rcp_f32_e32 v157, v133
	v_mul_f32_e32 v129, 0x3fb8aa3b, v121
	v_add_f32_e32 v104, 1.0, v104
	v_rcp_f32_e32 v128, v104
	v_mul_f32_e32 v104, 0x3fb8aa3b, v119
	v_exp_f32_e32 v104, v104
	v_mul_f32_e32 v133, 0x3fb8aa3b, v117
	v_exp_f32_e32 v129, v129
	v_exp_f32_e32 v133, v133
	v_add_f32_e32 v104, 1.0, v104
	v_rcp_f32_e32 v125, v104
	global_load_dwordx4 v[104:107], v[148:149], off offset:16
	global_load_dwordx4 v[108:111], v[148:149], off
	v_add_f32_e32 v129, 1.0, v129
	v_add_f32_e32 v133, 1.0, v133
	v_rcp_f32_e32 v129, v129
	v_rcp_f32_e32 v133, v133
	s_waitcnt vmcnt(1)
	v_pk_add_f32 v[134:135], v[104:105], 1.0 op_sel_hi:[1,0] neg_lo:[1,0] neg_hi:[1,0]
	s_waitcnt vmcnt(0)
	v_pk_add_f32 v[126:127], v[108:109], 1.0 op_sel_hi:[1,0] neg_lo:[1,0] neg_hi:[1,0]
	v_pk_add_f32 v[130:131], v[110:111], 1.0 op_sel_hi:[1,0] neg_lo:[1,0] neg_hi:[1,0]
	v_fma_f32 v108, v115, v126, v108
	v_max_f32_e32 v108, 0xda24260, v108
	v_fma_f32 v109, v128, v127, v109
	v_max_f32_e32 v109, 0xda24260, v109
	v_log_f32_e32 v108, v108
	v_fmac_f32_e32 v111, v132, v131
	v_max_f32_e32 v111, 0xda24260, v111
	v_pk_add_f32 v[182:183], v[106:107], 1.0 op_sel_hi:[1,0] neg_lo:[1,0] neg_hi:[1,0]
	v_mul_f32_e32 v115, 0x3f317217, v108
	v_fma_f32 v115, v108, s95, -v115
	v_fmac_f32_e32 v115, 0x3377d1cf, v108
	v_fmac_f32_e32 v115, 0x3f317217, v108
	v_cmp_lt_f32_e64 s[46:47], |v108|, s62
	v_mul_f32_e32 v128, 0x3fb8aa3b, v120
	v_mul_f32_e32 v132, 0x3fb8aa3b, v116
	v_cndmask_b32_e64 v108, v108, v115, s[46:47]
	v_exp_f32_e32 v128, v128
	v_log_f32_e32 v109, v109
	v_exp_f32_e32 v132, v132
	v_add_f32_e32 v128, 1.0, v128
	v_rcp_f32_e32 v128, v128
	v_mul_f32_e32 v115, 0x3f317217, v109
	v_fma_f32 v115, v109, s95, -v115
	v_fmac_f32_e32 v115, 0x3377d1cf, v109
	v_fmac_f32_e32 v115, 0x3f317217, v109
	v_cmp_lt_f32_e64 s[46:47], |v109|, s62
	v_add_f32_e32 v132, 1.0, v132
	v_rcp_f32_e32 v132, v132
	v_cndmask_b32_e64 v109, v109, v115, s[46:47]
	v_mul_f32_e32 v115, 0xbfb8aa3b, v120
	v_exp_f32_e32 v115, v115
	v_pk_mul_f32 v[126:127], v[124:125], v[126:127]
	v_pk_mul_f32 v[124:125], v[128:129], v[130:131]
	v_lshl_add_u64 v[128:129], v[146:147], 0, v[112:113]
	v_add_f32_e32 v115, 1.0, v115
	v_rcp_f32_e32 v115, v115
	s_nop 0
	v_fma_f32 v110, v115, v130, v110
	v_max_f32_e32 v110, 0xda24260, v110
	s_nop 1
	v_log_f32_e32 v110, v110
	s_nop 0
	v_mul_f32_e32 v115, 0x3f317217, v110
	v_fma_f32 v115, v110, s95, -v115
	v_fmac_f32_e32 v115, 0x3377d1cf, v110
	v_fmac_f32_e32 v115, 0x3f317217, v110
	v_cmp_lt_f32_e64 s[46:47], |v110|, s62
	s_nop 1
	v_cndmask_b32_e64 v110, v110, v115, s[46:47]
	s_nop 0
	v_log_f32_e32 v111, v111
	s_nop 0
	v_mul_f32_e32 v115, 0x3f317217, v111
	v_fma_f32 v115, v111, s95, -v115
	v_fmac_f32_e32 v115, 0x3377d1cf, v111
	v_fmac_f32_e32 v115, 0x3f317217, v111
	v_cmp_lt_f32_e64 s[46:47], |v111|, s62
	s_nop 1
	v_cndmask_b32_e64 v111, v111, v115, s[46:47]
	v_mul_f32_e32 v115, 0xbfb8aa3b, v116
	v_exp_f32_e32 v115, v115
	s_nop 0
	v_add_f32_e32 v115, 1.0, v115
	v_rcp_f32_e32 v115, v115
	s_nop 0
	v_fma_f32 v104, v115, v134, v104
	v_max_f32_e32 v104, 0xda24260, v104
	s_nop 1
	v_log_f32_e32 v104, v104
	s_nop 0
	v_mul_f32_e32 v115, 0x3f317217, v104
	v_fma_f32 v115, v104, s95, -v115
	v_fmac_f32_e32 v115, 0x3377d1cf, v104
	v_fmac_f32_e32 v115, 0x3f317217, v104
	v_cmp_lt_f32_e64 s[46:47], |v104|, s62
	s_nop 1
	v_cndmask_b32_e64 v104, v104, v115, s[46:47]
	v_mov_b32_e32 v178, v104
	v_fma_f32 v104, v157, v135, v105
	v_max_f32_e32 v104, 0xda24260, v104
	s_nop 1
	v_log_f32_e32 v104, v104
	s_nop 0
	v_mul_f32_e32 v105, 0x3f317217, v104
	v_fma_f32 v105, v104, s95, -v105
	v_fmac_f32_e32 v105, 0x3377d1cf, v104
	v_fmac_f32_e32 v105, 0x3f317217, v104
	v_cmp_lt_f32_e64 s[46:47], |v104|, s62
	s_nop 1
	v_cndmask_b32_e64 v104, v104, v105, s[46:47]
	v_mov_b32_e32 v179, v104
	v_mul_f32_e32 v104, 0xbfb8aa3b, v122
	v_exp_f32_e32 v104, v104
	v_mul_f32_e32 v105, 0xbfb8aa3b, v123
	v_exp_f32_e32 v105, v105
	v_add_f32_e32 v104, 1.0, v104
	v_rcp_f32_e32 v115, v104
	v_add_f32_e32 v105, 1.0, v105
	v_rcp_f32_e32 v157, v105
	v_mul_f32_e32 v104, 0x3fb8aa3b, v122
	v_fma_f32 v106, v115, v182, v106
	v_max_f32_e32 v106, 0xda24260, v106
	v_fmac_f32_e32 v107, v157, v183
	v_mul_f32_e32 v105, 0x3fb8aa3b, v123
	v_log_f32_e32 v106, v106
	v_exp_f32_e32 v104, v104
	v_exp_f32_e32 v105, v105
	v_mul_f32_e32 v115, 0x3f317217, v106
	v_fma_f32 v115, v106, s95, -v115
	v_fmac_f32_e32 v115, 0x3377d1cf, v106
	v_fmac_f32_e32 v115, 0x3f317217, v106
	v_cmp_lt_f32_e64 s[46:47], |v106|, s62
	v_add_f32_e32 v104, 1.0, v104
	v_add_f32_e32 v105, 1.0, v105
	v_cndmask_b32_e64 v106, v106, v115, s[46:47]
	v_mov_b32_e32 v180, v106
	v_max_f32_e32 v106, 0xda24260, v107
	v_rcp_f32_e32 v104, v104
	v_rcp_f32_e32 v105, v105
	v_log_f32_e32 v106, v106
	v_pk_mul_f32 v[104:105], v[104:105], v[182:183]
	v_mul_f32_e32 v107, 0x3f317217, v106
	v_fma_f32 v107, v106, s95, -v107
	v_fmac_f32_e32 v107, 0x3377d1cf, v106
	v_fmac_f32_e32 v107, 0x3f317217, v106
	v_cmp_lt_f32_e64 s[46:47], |v106|, s62
	s_nop 1
	v_cndmask_b32_e64 v106, v106, v107, s[46:47]
	v_mov_b32_e32 v181, v106
	v_pk_mul_f32 v[106:107], v[132:133], v[134:135]
	global_store_dwordx4 v[128:129], v[108:111], off
	global_store_dwordx4 v[128:129], v[178:181], off offset:16

.LBB0_372:
	s_andn2_b64 vcc, exec, s[36:37]
	s_cbranch_vccnz .LBB0_374
	global_load_dwordx4 v[96:99], v[148:149], off offset:528
	global_load_dwordx4 v[100:103], v[148:149], off offset:512
	v_mul_f32_e32 v116, 0xbfb8aa3b, v108
	v_exp_f32_e32 v116, v116
	v_mul_f32_e32 v117, 0xbfb8aa3b, v109
	v_exp_f32_e32 v117, v117
	v_lshl_add_u64 v[112:113], v[150:151], 0, v[112:113]
	v_add_f32_e32 v116, 1.0, v116
	v_rcp_f32_e32 v120, v116
	v_add_f32_e32 v117, 1.0, v117
	v_rcp_f32_e32 v121, v117
	v_mul_f32_e32 v116, 0x3fb8aa3b, v108
	v_mul_f32_e32 v117, 0x3fb8aa3b, v109
	v_exp_f32_e32 v116, v116
	v_exp_f32_e32 v117, v117
	v_add_f32_e32 v116, 1.0, v116
	v_add_f32_e32 v117, 1.0, v117
	v_rcp_f32_e32 v116, v116
	v_rcp_f32_e32 v117, v117
	s_waitcnt vmcnt(1)
	v_pk_add_f32 v[130:131], v[96:97], 1.0 op_sel_hi:[1,0] neg_lo:[1,0] neg_hi:[1,0]
	s_waitcnt vmcnt(0)
	v_pk_add_f32 v[118:119], v[100:101], 1.0 op_sel_hi:[1,0] neg_lo:[1,0] neg_hi:[1,0]
	v_pk_add_f32 v[122:123], v[102:103], 1.0 op_sel_hi:[1,0] neg_lo:[1,0] neg_hi:[1,0]
	v_fma_f32 v100, v120, v118, v100
	v_max_f32_e32 v100, 0xda24260, v100
	v_fma_f32 v101, v121, v119, v101
	v_max_f32_e32 v101, 0xda24260, v101
	v_log_f32_e32 v100, v100
	v_mul_f32_e32 v121, 0xbfb8aa3b, v111
	v_exp_f32_e32 v121, v121
	v_pk_add_f32 v[132:133], v[98:99], 1.0 op_sel_hi:[1,0] neg_lo:[1,0] neg_hi:[1,0]
	v_mul_f32_e32 v120, 0x3f317217, v100
	v_fma_f32 v120, v100, s95, -v120
	v_fmac_f32_e32 v120, 0x3377d1cf, v100
	v_fmac_f32_e32 v120, 0x3f317217, v100
	v_cmp_lt_f32_e64 s[46:47], |v100|, s62
	v_add_f32_e32 v121, 1.0, v121
	v_rcp_f32_e32 v125, v121
	v_cndmask_b32_e64 v100, v100, v120, s[46:47]
	v_fmac_f32_e32 v103, v125, v123
	v_log_f32_e32 v101, v101
	v_max_f32_e32 v103, 0xda24260, v103
	v_mul_f32_e32 v125, 0xbfb8aa3b, v107
	v_exp_f32_e32 v125, v125
	v_mul_f32_e32 v120, 0x3f317217, v101
	v_fma_f32 v120, v101, s95, -v120
	v_fmac_f32_e32 v120, 0x3377d1cf, v101
	v_fmac_f32_e32 v120, 0x3f317217, v101
	v_cmp_lt_f32_e64 s[46:47], |v101|, s62
	v_add_f32_e32 v125, 1.0, v125
	v_rcp_f32_e32 v127, v125
	v_cndmask_b32_e64 v101, v101, v120, s[46:47]
	v_mul_f32_e32 v120, 0xbfb8aa3b, v110
	v_exp_f32_e32 v120, v120
	v_mul_f32_e32 v121, 0x3fb8aa3b, v111
	v_mul_f32_e32 v125, 0x3fb8aa3b, v107
	v_exp_f32_e32 v121, v121
	v_add_f32_e32 v120, 1.0, v120
	v_rcp_f32_e32 v124, v120
	v_mul_f32_e32 v120, 0x3fb8aa3b, v110
	v_exp_f32_e32 v120, v120
	v_exp_f32_e32 v125, v125
	v_fma_f32 v102, v124, v122, v102
	v_max_f32_e32 v102, 0xda24260, v102
	v_add_f32_e32 v120, 1.0, v120
	v_add_f32_e32 v121, 1.0, v121
	v_log_f32_e32 v102, v102
	v_add_f32_e32 v125, 1.0, v125
	v_rcp_f32_e32 v120, v120
	v_rcp_f32_e32 v121, v121
	v_mul_f32_e32 v124, 0x3f317217, v102
	v_fma_f32 v124, v102, s95, -v124
	v_fmac_f32_e32 v124, 0x3377d1cf, v102
	v_fmac_f32_e32 v124, 0x3f317217, v102
	v_cmp_lt_f32_e64 s[46:47], |v102|, s62
	v_rcp_f32_e32 v125, v125
	v_pk_mul_f32 v[118:119], v[116:117], v[118:119]
	v_cndmask_b32_e64 v102, v102, v124, s[46:47]
	v_pk_mul_f32 v[116:117], v[120:121], v[122:123]
	v_log_f32_e32 v103, v103
	s_nop 0
	v_mul_f32_e32 v124, 0x3f317217, v103
	v_fma_f32 v124, v103, s95, -v124
	v_fmac_f32_e32 v124, 0x3377d1cf, v103
	v_fmac_f32_e32 v124, 0x3f317217, v103
	v_cmp_lt_f32_e64 s[46:47], |v103|, s62
	s_nop 1
	v_cndmask_b32_e64 v103, v103, v124, s[46:47]
	v_mul_f32_e32 v124, 0xbfb8aa3b, v106
	v_exp_f32_e32 v124, v124
	s_nop 0
	v_add_f32_e32 v124, 1.0, v124
	v_rcp_f32_e32 v126, v124
	v_mul_f32_e32 v124, 0x3fb8aa3b, v106
	v_exp_f32_e32 v124, v124
	v_fma_f32 v96, v126, v130, v96
	v_max_f32_e32 v96, 0xda24260, v96
	v_add_f32_e32 v124, 1.0, v124
	v_rcp_f32_e32 v124, v124
	v_log_f32_e32 v96, v96
	s_nop 0
	v_mul_f32_e32 v126, 0x3f317217, v96
	v_fma_f32 v126, v96, s95, -v126
	v_fmac_f32_e32 v126, 0x3377d1cf, v96
	v_fmac_f32_e32 v126, 0x3f317217, v96
	v_cmp_lt_f32_e64 s[46:47], |v96|, s62
	s_nop 1
	v_cndmask_b32_e64 v96, v96, v126, s[46:47]
	v_mov_b32_e32 v126, v96
	v_fma_f32 v96, v127, v131, v97
	v_max_f32_e32 v96, 0xda24260, v96
	s_nop 1
	v_log_f32_e32 v96, v96
	s_nop 0
	v_mul_f32_e32 v97, 0x3f317217, v96
	v_fma_f32 v97, v96, s95, -v97
	v_fmac_f32_e32 v97, 0x3377d1cf, v96
	v_fmac_f32_e32 v97, 0x3f317217, v96
	v_cmp_lt_f32_e64 s[46:47], |v96|, s62
	s_nop 1
	v_cndmask_b32_e64 v96, v96, v97, s[46:47]
	v_mov_b32_e32 v127, v96
	v_mul_f32_e32 v96, 0xbfb8aa3b, v114
	v_exp_f32_e32 v96, v96
	v_mul_f32_e32 v97, 0xbfb8aa3b, v115
	v_exp_f32_e32 v97, v97
	v_add_f32_e32 v96, 1.0, v96
	v_rcp_f32_e32 v128, v96
	v_add_f32_e32 v97, 1.0, v97
	v_rcp_f32_e32 v129, v97
	v_mul_f32_e32 v96, 0x3fb8aa3b, v114
	v_fma_f32 v98, v128, v132, v98
	v_max_f32_e32 v98, 0xda24260, v98
	v_fmac_f32_e32 v99, v129, v133
	v_mul_f32_e32 v97, 0x3fb8aa3b, v115
	v_log_f32_e32 v98, v98
	v_exp_f32_e32 v96, v96
	v_exp_f32_e32 v97, v97
	v_mul_f32_e32 v128, 0x3f317217, v98
	v_fma_f32 v128, v98, s95, -v128
	v_fmac_f32_e32 v128, 0x3377d1cf, v98
	v_fmac_f32_e32 v128, 0x3f317217, v98
	v_cmp_lt_f32_e64 s[46:47], |v98|, s62
	v_add_f32_e32 v96, 1.0, v96
	v_add_f32_e32 v97, 1.0, v97
	v_cndmask_b32_e64 v98, v98, v128, s[46:47]
	v_mov_b32_e32 v128, v98
	v_max_f32_e32 v98, 0xda24260, v99
	v_rcp_f32_e32 v96, v96
	v_rcp_f32_e32 v97, v97
	v_log_f32_e32 v98, v98
	v_pk_mul_f32 v[96:97], v[96:97], v[132:133]
	v_mul_f32_e32 v99, 0x3f317217, v98
	v_fma_f32 v99, v98, s95, -v99
	v_fmac_f32_e32 v99, 0x3377d1cf, v98
	v_fmac_f32_e32 v99, 0x3f317217, v98
	v_cmp_lt_f32_e64 s[46:47], |v98|, s62
	s_nop 1
	v_cndmask_b32_e64 v98, v98, v99, s[46:47]
	v_mov_b32_e32 v129, v98
	v_pk_mul_f32 v[98:99], v[124:125], v[130:131]
	global_store_dwordx4 v[112:113], v[100:103], off
	global_store_dwordx4 v[112:113], v[126:129], off offset:16

.LBB0_384:
	s_andn2_b64 vcc, exec, s[36:37]
	s_cbranch_vccnz .LBB0_386
	v_mul_f32_e32 v96, 0xbfb8aa3b, v108
	v_exp_f32_e32 v96, v96
	s_nop 0
	v_add_f32_e32 v96, 1.0, v96
	v_rcp_f32_e32 v118, v96
	v_mul_f32_e32 v96, 0x3fb8aa3b, v108
	v_exp_f32_e32 v96, v96
	s_nop 0
	v_add_f32_e32 v96, 1.0, v96
	v_rcp_f32_e32 v114, v96
	v_mul_f32_e32 v96, 0xbfb8aa3b, v109
	v_exp_f32_e32 v96, v96
	s_nop 0
	v_add_f32_e32 v96, 1.0, v96
	v_rcp_f32_e32 v119, v96
	v_mul_f32_e32 v96, 0x3fb8aa3b, v109
	v_exp_f32_e32 v96, v96
	s_nop 0
	v_add_f32_e32 v96, 1.0, v96
	v_rcp_f32_e32 v115, v96
	global_load_dwordx4 v[96:99], v[148:149], off offset:16
	global_load_dwordx4 v[100:103], v[148:149], off
	s_waitcnt vmcnt(1)
	v_pk_add_f32 v[128:129], v[96:97], 1.0 op_sel_hi:[1,0] neg_lo:[1,0] neg_hi:[1,0]
	s_waitcnt vmcnt(0)
	v_pk_add_f32 v[116:117], v[100:101], 1.0 op_sel_hi:[1,0] neg_lo:[1,0] neg_hi:[1,0]
	v_pk_add_f32 v[120:121], v[102:103], 1.0 op_sel_hi:[1,0] neg_lo:[1,0] neg_hi:[1,0]
	v_fma_f32 v100, v118, v116, v100
	v_max_f32_e32 v100, 0xda24260, v100
	v_fma_f32 v101, v119, v117, v101
	v_max_f32_e32 v101, 0xda24260, v101
	v_log_f32_e32 v100, v100
	v_mul_f32_e32 v119, 0xbfb8aa3b, v111
	v_exp_f32_e32 v119, v119
	v_pk_add_f32 v[130:131], v[98:99], 1.0 op_sel_hi:[1,0] neg_lo:[1,0] neg_hi:[1,0]
	v_mul_f32_e32 v118, 0x3f317217, v100
	v_fma_f32 v118, v100, s95, -v118
	v_fmac_f32_e32 v118, 0x3377d1cf, v100
	v_fmac_f32_e32 v118, 0x3f317217, v100
	v_cmp_lt_f32_e64 s[46:47], |v100|, s62
	v_add_f32_e32 v119, 1.0, v119
	v_rcp_f32_e32 v123, v119
	v_cndmask_b32_e64 v100, v100, v118, s[46:47]
	v_fmac_f32_e32 v103, v123, v121
	v_log_f32_e32 v101, v101
	v_max_f32_e32 v103, 0xda24260, v103
	v_mul_f32_e32 v123, 0xbfb8aa3b, v107
	v_exp_f32_e32 v123, v123
	v_mul_f32_e32 v118, 0x3f317217, v101
	v_fma_f32 v118, v101, s95, -v118
	v_fmac_f32_e32 v118, 0x3377d1cf, v101
	v_fmac_f32_e32 v118, 0x3f317217, v101
	v_cmp_lt_f32_e64 s[46:47], |v101|, s62
	v_add_f32_e32 v123, 1.0, v123
	v_rcp_f32_e32 v125, v123
	v_cndmask_b32_e64 v101, v101, v118, s[46:47]
	v_mul_f32_e32 v118, 0xbfb8aa3b, v110
	v_exp_f32_e32 v118, v118
	v_mul_f32_e32 v119, 0x3fb8aa3b, v111
	v_mul_f32_e32 v123, 0x3fb8aa3b, v107
	v_exp_f32_e32 v119, v119
	v_add_f32_e32 v118, 1.0, v118
	v_rcp_f32_e32 v122, v118
	v_mul_f32_e32 v118, 0x3fb8aa3b, v110
	v_exp_f32_e32 v118, v118
	v_exp_f32_e32 v123, v123
	v_fma_f32 v102, v122, v120, v102
	v_max_f32_e32 v102, 0xda24260, v102
	v_add_f32_e32 v118, 1.0, v118
	v_add_f32_e32 v119, 1.0, v119
	v_log_f32_e32 v102, v102
	v_add_f32_e32 v123, 1.0, v123
	v_rcp_f32_e32 v118, v118
	v_rcp_f32_e32 v119, v119
	v_mul_f32_e32 v122, 0x3f317217, v102
	v_fma_f32 v122, v102, s95, -v122
	v_fmac_f32_e32 v122, 0x3377d1cf, v102
	v_fmac_f32_e32 v122, 0x3f317217, v102
	v_cmp_lt_f32_e64 s[46:47], |v102|, s62
	v_rcp_f32_e32 v123, v123
	v_pk_mul_f32 v[116:117], v[114:115], v[116:117]
	v_cndmask_b32_e64 v102, v102, v122, s[46:47]
	v_pk_mul_f32 v[114:115], v[118:119], v[120:121]
	v_log_f32_e32 v103, v103
	v_lshl_add_u64 v[118:119], v[146:147], 0, v[104:105]
	v_mul_f32_e32 v122, 0x3f317217, v103
	v_fma_f32 v122, v103, s95, -v122
	v_fmac_f32_e32 v122, 0x3377d1cf, v103
	v_fmac_f32_e32 v122, 0x3f317217, v103
	v_cmp_lt_f32_e64 s[46:47], |v103|, s62
	s_nop 1
	v_cndmask_b32_e64 v103, v103, v122, s[46:47]
	v_mul_f32_e32 v122, 0xbfb8aa3b, v106
	v_exp_f32_e32 v122, v122
	s_nop 0
	v_add_f32_e32 v122, 1.0, v122
	v_rcp_f32_e32 v124, v122
	v_mul_f32_e32 v122, 0x3fb8aa3b, v106
	v_exp_f32_e32 v122, v122
	v_fma_f32 v96, v124, v128, v96
	v_max_f32_e32 v96, 0xda24260, v96
	v_add_f32_e32 v122, 1.0, v122
	v_rcp_f32_e32 v122, v122
	v_log_f32_e32 v96, v96
	s_nop 0
	v_mul_f32_e32 v124, 0x3f317217, v96
	v_fma_f32 v124, v96, s95, -v124
	v_fmac_f32_e32 v124, 0x3377d1cf, v96
	v_fmac_f32_e32 v124, 0x3f317217, v96
	v_cmp_lt_f32_e64 s[46:47], |v96|, s62
	s_nop 1
	v_cndmask_b32_e64 v96, v96, v124, s[46:47]
	v_mov_b32_e32 v124, v96
	v_fma_f32 v96, v125, v129, v97
	v_max_f32_e32 v96, 0xda24260, v96
	s_nop 1
	v_log_f32_e32 v96, v96
	s_nop 0
	v_mul_f32_e32 v97, 0x3f317217, v96
	v_fma_f32 v97, v96, s95, -v97
	v_fmac_f32_e32 v97, 0x3377d1cf, v96
	v_fmac_f32_e32 v97, 0x3f317217, v96
	v_cmp_lt_f32_e64 s[46:47], |v96|, s62
	s_nop 1
	v_cndmask_b32_e64 v96, v96, v97, s[46:47]
	v_mov_b32_e32 v125, v96
	v_mul_f32_e32 v96, 0xbfb8aa3b, v112
	v_exp_f32_e32 v96, v96
	v_mul_f32_e32 v97, 0xbfb8aa3b, v113
	v_exp_f32_e32 v97, v97
	v_add_f32_e32 v96, 1.0, v96
	v_rcp_f32_e32 v126, v96
	v_add_f32_e32 v97, 1.0, v97
	v_rcp_f32_e32 v127, v97
	v_mul_f32_e32 v96, 0x3fb8aa3b, v112
	v_fma_f32 v98, v126, v130, v98
	v_max_f32_e32 v98, 0xda24260, v98
	v_fmac_f32_e32 v99, v127, v131
	v_mul_f32_e32 v97, 0x3fb8aa3b, v113
	v_log_f32_e32 v98, v98
	v_exp_f32_e32 v96, v96
	v_exp_f32_e32 v97, v97
	v_mul_f32_e32 v126, 0x3f317217, v98
	v_fma_f32 v126, v98, s95, -v126
	v_fmac_f32_e32 v126, 0x3377d1cf, v98
	v_fmac_f32_e32 v126, 0x3f317217, v98
	v_cmp_lt_f32_e64 s[46:47], |v98|, s62
	v_add_f32_e32 v96, 1.0, v96
	v_add_f32_e32 v97, 1.0, v97
	v_cndmask_b32_e64 v98, v98, v126, s[46:47]
	v_mov_b32_e32 v126, v98
	v_max_f32_e32 v98, 0xda24260, v99
	v_rcp_f32_e32 v96, v96
	v_rcp_f32_e32 v97, v97
	v_log_f32_e32 v98, v98
	v_pk_mul_f32 v[96:97], v[96:97], v[130:131]
	v_mul_f32_e32 v99, 0x3f317217, v98
	v_fma_f32 v99, v98, s95, -v99
	v_fmac_f32_e32 v99, 0x3377d1cf, v98
	v_fmac_f32_e32 v99, 0x3f317217, v98
	v_cmp_lt_f32_e64 s[46:47], |v98|, s62
	s_nop 1
	v_cndmask_b32_e64 v98, v98, v99, s[46:47]
	v_mov_b32_e32 v127, v98
	v_pk_mul_f32 v[98:99], v[122:123], v[128:129]
	global_store_dwordx4 v[118:119], v[100:103], off
	global_store_dwordx4 v[118:119], v[124:127], off offset:16

.LBB0_396:
	s_andn2_b64 vcc, exec, s[36:37]
	s_cbranch_vccnz .LBB0_398
	global_load_dwordx4 v[88:91], v[148:149], off offset:528
	global_load_dwordx4 v[92:95], v[148:149], off offset:512
	v_mul_f32_e32 v108, 0xbfb8aa3b, v100
	v_exp_f32_e32 v108, v108
	v_mul_f32_e32 v109, 0xbfb8aa3b, v101
	v_exp_f32_e32 v109, v109
	v_lshl_add_u64 v[104:105], v[150:151], 0, v[104:105]
	v_add_f32_e32 v108, 1.0, v108
	v_rcp_f32_e32 v112, v108
	v_add_f32_e32 v109, 1.0, v109
	v_rcp_f32_e32 v113, v109
	v_mul_f32_e32 v108, 0x3fb8aa3b, v100
	v_mul_f32_e32 v109, 0x3fb8aa3b, v101
	v_exp_f32_e32 v108, v108
	v_exp_f32_e32 v109, v109
	v_add_f32_e32 v108, 1.0, v108
	v_add_f32_e32 v109, 1.0, v109
	v_rcp_f32_e32 v108, v108
	v_rcp_f32_e32 v109, v109
	s_waitcnt vmcnt(1)
	v_pk_add_f32 v[122:123], v[88:89], 1.0 op_sel_hi:[1,0] neg_lo:[1,0] neg_hi:[1,0]
	s_waitcnt vmcnt(0)
	v_pk_add_f32 v[110:111], v[92:93], 1.0 op_sel_hi:[1,0] neg_lo:[1,0] neg_hi:[1,0]
	v_pk_add_f32 v[114:115], v[94:95], 1.0 op_sel_hi:[1,0] neg_lo:[1,0] neg_hi:[1,0]
	v_fma_f32 v92, v112, v110, v92
	v_max_f32_e32 v92, 0xda24260, v92
	v_fma_f32 v93, v113, v111, v93
	v_max_f32_e32 v93, 0xda24260, v93
	v_log_f32_e32 v92, v92
	v_mul_f32_e32 v113, 0xbfb8aa3b, v103
	v_exp_f32_e32 v113, v113
	v_pk_add_f32 v[124:125], v[90:91], 1.0 op_sel_hi:[1,0] neg_lo:[1,0] neg_hi:[1,0]
	v_mul_f32_e32 v112, 0x3f317217, v92
	v_fma_f32 v112, v92, s95, -v112
	v_fmac_f32_e32 v112, 0x3377d1cf, v92
	v_fmac_f32_e32 v112, 0x3f317217, v92
	v_cmp_lt_f32_e64 s[46:47], |v92|, s62
	v_add_f32_e32 v113, 1.0, v113
	v_rcp_f32_e32 v117, v113
	v_cndmask_b32_e64 v92, v92, v112, s[46:47]
	v_fmac_f32_e32 v95, v117, v115
	v_log_f32_e32 v93, v93
	v_max_f32_e32 v95, 0xda24260, v95
	v_mul_f32_e32 v117, 0xbfb8aa3b, v99
	v_exp_f32_e32 v117, v117
	v_mul_f32_e32 v112, 0x3f317217, v93
	v_fma_f32 v112, v93, s95, -v112
	v_fmac_f32_e32 v112, 0x3377d1cf, v93
	v_fmac_f32_e32 v112, 0x3f317217, v93
	v_cmp_lt_f32_e64 s[46:47], |v93|, s62
	v_add_f32_e32 v117, 1.0, v117
	v_rcp_f32_e32 v119, v117
	v_cndmask_b32_e64 v93, v93, v112, s[46:47]
	v_mul_f32_e32 v112, 0xbfb8aa3b, v102
	v_exp_f32_e32 v112, v112
	v_mul_f32_e32 v113, 0x3fb8aa3b, v103
	v_mul_f32_e32 v117, 0x3fb8aa3b, v99
	v_exp_f32_e32 v113, v113
	v_add_f32_e32 v112, 1.0, v112
	v_rcp_f32_e32 v116, v112
	v_mul_f32_e32 v112, 0x3fb8aa3b, v102
	v_exp_f32_e32 v112, v112
	v_exp_f32_e32 v117, v117
	v_fma_f32 v94, v116, v114, v94
	v_max_f32_e32 v94, 0xda24260, v94
	v_add_f32_e32 v112, 1.0, v112
	v_add_f32_e32 v113, 1.0, v113
	v_log_f32_e32 v94, v94
	v_add_f32_e32 v117, 1.0, v117
	v_rcp_f32_e32 v112, v112
	v_rcp_f32_e32 v113, v113
	v_mul_f32_e32 v116, 0x3f317217, v94
	v_fma_f32 v116, v94, s95, -v116
	v_fmac_f32_e32 v116, 0x3377d1cf, v94
	v_fmac_f32_e32 v116, 0x3f317217, v94
	v_cmp_lt_f32_e64 s[46:47], |v94|, s62
	v_rcp_f32_e32 v117, v117
	v_pk_mul_f32 v[110:111], v[108:109], v[110:111]
	v_cndmask_b32_e64 v94, v94, v116, s[46:47]
	v_pk_mul_f32 v[108:109], v[112:113], v[114:115]
	v_log_f32_e32 v95, v95
	s_nop 0
	v_mul_f32_e32 v116, 0x3f317217, v95
	v_fma_f32 v116, v95, s95, -v116
	v_fmac_f32_e32 v116, 0x3377d1cf, v95
	v_fmac_f32_e32 v116, 0x3f317217, v95
	v_cmp_lt_f32_e64 s[46:47], |v95|, s62
	s_nop 1
	v_cndmask_b32_e64 v95, v95, v116, s[46:47]
	v_mul_f32_e32 v116, 0xbfb8aa3b, v98
	v_exp_f32_e32 v116, v116
	s_nop 0
	v_add_f32_e32 v116, 1.0, v116
	v_rcp_f32_e32 v118, v116
	v_mul_f32_e32 v116, 0x3fb8aa3b, v98
	v_exp_f32_e32 v116, v116
	v_fma_f32 v88, v118, v122, v88
	v_max_f32_e32 v88, 0xda24260, v88
	v_add_f32_e32 v116, 1.0, v116
	v_rcp_f32_e32 v116, v116
	v_log_f32_e32 v88, v88
	s_nop 0
	v_mul_f32_e32 v118, 0x3f317217, v88
	v_fma_f32 v118, v88, s95, -v118
	v_fmac_f32_e32 v118, 0x3377d1cf, v88
	v_fmac_f32_e32 v118, 0x3f317217, v88
	v_cmp_lt_f32_e64 s[46:47], |v88|, s62
	s_nop 1
	v_cndmask_b32_e64 v88, v88, v118, s[46:47]
	v_mov_b32_e32 v118, v88
	v_fma_f32 v88, v119, v123, v89
	v_max_f32_e32 v88, 0xda24260, v88
	s_nop 1
	v_log_f32_e32 v88, v88
	s_nop 0
	v_mul_f32_e32 v89, 0x3f317217, v88
	v_fma_f32 v89, v88, s95, -v89
	v_fmac_f32_e32 v89, 0x3377d1cf, v88
	v_fmac_f32_e32 v89, 0x3f317217, v88
	v_cmp_lt_f32_e64 s[46:47], |v88|, s62
	s_nop 1
	v_cndmask_b32_e64 v88, v88, v89, s[46:47]
	v_mov_b32_e32 v119, v88
	v_mul_f32_e32 v88, 0xbfb8aa3b, v106
	v_exp_f32_e32 v88, v88
	v_mul_f32_e32 v89, 0xbfb8aa3b, v107
	v_exp_f32_e32 v89, v89
	v_add_f32_e32 v88, 1.0, v88
	v_rcp_f32_e32 v120, v88
	v_add_f32_e32 v89, 1.0, v89
	v_rcp_f32_e32 v121, v89
	v_mul_f32_e32 v88, 0x3fb8aa3b, v106
	v_fma_f32 v90, v120, v124, v90
	v_max_f32_e32 v90, 0xda24260, v90
	v_fmac_f32_e32 v91, v121, v125
	v_mul_f32_e32 v89, 0x3fb8aa3b, v107
	v_log_f32_e32 v90, v90
	v_exp_f32_e32 v88, v88
	v_exp_f32_e32 v89, v89
	v_mul_f32_e32 v120, 0x3f317217, v90
	v_fma_f32 v120, v90, s95, -v120
	v_fmac_f32_e32 v120, 0x3377d1cf, v90
	v_fmac_f32_e32 v120, 0x3f317217, v90
	v_cmp_lt_f32_e64 s[46:47], |v90|, s62
	v_add_f32_e32 v88, 1.0, v88
	v_add_f32_e32 v89, 1.0, v89
	v_cndmask_b32_e64 v90, v90, v120, s[46:47]
	v_mov_b32_e32 v120, v90
	v_max_f32_e32 v90, 0xda24260, v91
	v_rcp_f32_e32 v88, v88
	v_rcp_f32_e32 v89, v89
	v_log_f32_e32 v90, v90
	v_pk_mul_f32 v[88:89], v[88:89], v[124:125]
	v_mul_f32_e32 v91, 0x3f317217, v90
	v_fma_f32 v91, v90, s95, -v91
	v_fmac_f32_e32 v91, 0x3377d1cf, v90
	v_fmac_f32_e32 v91, 0x3f317217, v90
	v_cmp_lt_f32_e64 s[46:47], |v90|, s62
	s_nop 1
	v_cndmask_b32_e64 v90, v90, v91, s[46:47]
	v_mov_b32_e32 v121, v90
	v_pk_mul_f32 v[90:91], v[116:117], v[122:123]
	global_store_dwordx4 v[104:105], v[92:95], off
	global_store_dwordx4 v[104:105], v[118:121], off offset:16

.LBB0_408:
	s_andn2_b64 vcc, exec, s[36:37]
	s_cbranch_vccnz .LBB0_410
	v_mul_f32_e32 v88, 0xbfb8aa3b, v102
	v_exp_f32_e32 v88, v88
	v_mul_f32_e32 v113, 0xbfb8aa3b, v105
	v_exp_f32_e32 v113, v113
	v_mul_f32_e32 v117, 0xbfb8aa3b, v101
	v_add_f32_e32 v88, 1.0, v88
	v_rcp_f32_e32 v99, v88
	v_mul_f32_e32 v88, 0x3fb8aa3b, v102
	v_exp_f32_e32 v88, v88
	v_add_f32_e32 v113, 1.0, v113
	v_rcp_f32_e32 v116, v113
	v_exp_f32_e32 v117, v117
	v_add_f32_e32 v88, 1.0, v88
	v_rcp_f32_e32 v108, v88
	v_mul_f32_e32 v88, 0xbfb8aa3b, v103
	v_exp_f32_e32 v88, v88
	v_add_f32_e32 v117, 1.0, v117
	v_rcp_f32_e32 v119, v117
	v_mul_f32_e32 v113, 0x3fb8aa3b, v105
	v_add_f32_e32 v88, 1.0, v88
	v_rcp_f32_e32 v112, v88
	v_mul_f32_e32 v88, 0x3fb8aa3b, v103
	v_exp_f32_e32 v88, v88
	v_mul_f32_e32 v117, 0x3fb8aa3b, v101
	v_exp_f32_e32 v113, v113
	v_exp_f32_e32 v117, v117
	v_add_f32_e32 v88, 1.0, v88
	v_rcp_f32_e32 v109, v88
	global_load_dwordx4 v[88:91], v[148:149], off offset:16
	global_load_dwordx4 v[92:95], v[148:149], off
	v_add_f32_e32 v113, 1.0, v113
	v_add_f32_e32 v117, 1.0, v117
	v_rcp_f32_e32 v113, v113
	v_rcp_f32_e32 v117, v117
	s_waitcnt vmcnt(1)
	v_pk_add_f32 v[122:123], v[88:89], 1.0 op_sel_hi:[1,0] neg_lo:[1,0] neg_hi:[1,0]
	s_waitcnt vmcnt(0)
	v_pk_add_f32 v[110:111], v[92:93], 1.0 op_sel_hi:[1,0] neg_lo:[1,0] neg_hi:[1,0]
	v_pk_add_f32 v[114:115], v[94:95], 1.0 op_sel_hi:[1,0] neg_lo:[1,0] neg_hi:[1,0]
	v_fma_f32 v92, v99, v110, v92
	v_max_f32_e32 v92, 0xda24260, v92
	v_fma_f32 v93, v112, v111, v93
	v_max_f32_e32 v93, 0xda24260, v93
	v_log_f32_e32 v92, v92
	v_fmac_f32_e32 v95, v116, v115
	v_max_f32_e32 v95, 0xda24260, v95
	v_pk_add_f32 v[124:125], v[90:91], 1.0 op_sel_hi:[1,0] neg_lo:[1,0] neg_hi:[1,0]
	v_mul_f32_e32 v99, 0x3f317217, v92
	v_fma_f32 v99, v92, s95, -v99
	v_fmac_f32_e32 v99, 0x3377d1cf, v92
	v_fmac_f32_e32 v99, 0x3f317217, v92
	v_cmp_lt_f32_e64 s[46:47], |v92|, s62
	v_mul_f32_e32 v112, 0x3fb8aa3b, v104
	v_mul_f32_e32 v116, 0x3fb8aa3b, v100
	v_cndmask_b32_e64 v92, v92, v99, s[46:47]
	v_exp_f32_e32 v112, v112
	v_log_f32_e32 v93, v93
	v_exp_f32_e32 v116, v116
	v_add_f32_e32 v112, 1.0, v112
	v_rcp_f32_e32 v112, v112
	v_mul_f32_e32 v99, 0x3f317217, v93
	v_fma_f32 v99, v93, s95, -v99
	v_fmac_f32_e32 v99, 0x3377d1cf, v93
	v_fmac_f32_e32 v99, 0x3f317217, v93
	v_cmp_lt_f32_e64 s[46:47], |v93|, s62
	v_add_f32_e32 v116, 1.0, v116
	v_rcp_f32_e32 v116, v116
	v_cndmask_b32_e64 v93, v93, v99, s[46:47]
	v_mul_f32_e32 v99, 0xbfb8aa3b, v104
	v_exp_f32_e32 v99, v99
	v_pk_mul_f32 v[110:111], v[108:109], v[110:111]
	v_pk_mul_f32 v[108:109], v[112:113], v[114:115]
	v_lshl_add_u64 v[112:113], v[146:147], 0, v[96:97]
	v_add_f32_e32 v99, 1.0, v99
	v_rcp_f32_e32 v99, v99
	s_nop 0
	v_fma_f32 v94, v99, v114, v94
	v_max_f32_e32 v94, 0xda24260, v94
	s_nop 1
	v_log_f32_e32 v94, v94
	s_nop 0
	v_mul_f32_e32 v99, 0x3f317217, v94
	v_fma_f32 v99, v94, s95, -v99
	v_fmac_f32_e32 v99, 0x3377d1cf, v94
	v_fmac_f32_e32 v99, 0x3f317217, v94
	v_cmp_lt_f32_e64 s[46:47], |v94|, s62
	s_nop 1
	v_cndmask_b32_e64 v94, v94, v99, s[46:47]
	s_nop 0
	v_log_f32_e32 v95, v95
	s_nop 0
	v_mul_f32_e32 v99, 0x3f317217, v95
	v_fma_f32 v99, v95, s95, -v99
	v_fmac_f32_e32 v99, 0x3377d1cf, v95
	v_fmac_f32_e32 v99, 0x3f317217, v95
	v_cmp_lt_f32_e64 s[46:47], |v95|, s62
	s_nop 1
	v_cndmask_b32_e64 v95, v95, v99, s[46:47]
	v_mul_f32_e32 v99, 0xbfb8aa3b, v100
	v_exp_f32_e32 v99, v99
	s_nop 0
	v_add_f32_e32 v99, 1.0, v99
	v_rcp_f32_e32 v99, v99
	s_nop 0
	v_fma_f32 v88, v99, v122, v88
	v_max_f32_e32 v88, 0xda24260, v88
	s_nop 1
	v_log_f32_e32 v88, v88
	s_nop 0
	v_mul_f32_e32 v99, 0x3f317217, v88
	v_fma_f32 v99, v88, s95, -v99
	v_fmac_f32_e32 v99, 0x3377d1cf, v88
	v_fmac_f32_e32 v99, 0x3f317217, v88
	v_cmp_lt_f32_e64 s[46:47], |v88|, s62
	s_nop 1
	v_cndmask_b32_e64 v88, v88, v99, s[46:47]
	v_mov_b32_e32 v118, v88
	v_fma_f32 v88, v119, v123, v89
	v_max_f32_e32 v88, 0xda24260, v88
	s_nop 1
	v_log_f32_e32 v88, v88
	s_nop 0
	v_mul_f32_e32 v89, 0x3f317217, v88
	v_fma_f32 v89, v88, s95, -v89
	v_fmac_f32_e32 v89, 0x3377d1cf, v88
	v_fmac_f32_e32 v89, 0x3f317217, v88
	v_cmp_lt_f32_e64 s[46:47], |v88|, s62
	s_nop 1
	v_cndmask_b32_e64 v88, v88, v89, s[46:47]
	v_mov_b32_e32 v119, v88
	v_mul_f32_e32 v88, 0xbfb8aa3b, v106
	v_exp_f32_e32 v88, v88
	v_mul_f32_e32 v89, 0xbfb8aa3b, v107
	v_exp_f32_e32 v89, v89
	v_add_f32_e32 v88, 1.0, v88
	v_rcp_f32_e32 v99, v88
	v_add_f32_e32 v89, 1.0, v89
	v_rcp_f32_e32 v121, v89
	v_mul_f32_e32 v88, 0x3fb8aa3b, v106
	v_fma_f32 v90, v99, v124, v90
	v_max_f32_e32 v90, 0xda24260, v90
	v_fmac_f32_e32 v91, v121, v125
	v_mul_f32_e32 v89, 0x3fb8aa3b, v107
	v_log_f32_e32 v90, v90
	v_exp_f32_e32 v88, v88
	v_exp_f32_e32 v89, v89
	v_mul_f32_e32 v99, 0x3f317217, v90
	v_fma_f32 v99, v90, s95, -v99
	v_fmac_f32_e32 v99, 0x3377d1cf, v90
	v_fmac_f32_e32 v99, 0x3f317217, v90
	v_cmp_lt_f32_e64 s[46:47], |v90|, s62
	v_add_f32_e32 v88, 1.0, v88
	v_add_f32_e32 v89, 1.0, v89
	v_cndmask_b32_e64 v90, v90, v99, s[46:47]
	v_mov_b32_e32 v120, v90
	v_max_f32_e32 v90, 0xda24260, v91
	v_rcp_f32_e32 v88, v88
	v_rcp_f32_e32 v89, v89
	v_log_f32_e32 v90, v90
	v_pk_mul_f32 v[88:89], v[88:89], v[124:125]
	v_mul_f32_e32 v91, 0x3f317217, v90
	v_fma_f32 v91, v90, s95, -v91
	v_fmac_f32_e32 v91, 0x3377d1cf, v90
	v_fmac_f32_e32 v91, 0x3f317217, v90
	v_cmp_lt_f32_e64 s[46:47], |v90|, s62
	s_nop 1
	v_cndmask_b32_e64 v90, v90, v91, s[46:47]
	v_mov_b32_e32 v121, v90
	v_pk_mul_f32 v[90:91], v[116:117], v[122:123]
	global_store_dwordx4 v[112:113], v[92:95], off
	global_store_dwordx4 v[112:113], v[118:121], off offset:16

.LBB0_420:
	s_andn2_b64 vcc, exec, s[36:37]
	s_cbranch_vccnz .LBB0_422
	global_load_dwordx4 v[80:83], v[148:149], off offset:528
	global_load_dwordx4 v[84:87], v[148:149], off offset:512
	v_mul_f32_e32 v100, 0xbfb8aa3b, v92
	v_exp_f32_e32 v100, v100
	v_mul_f32_e32 v101, 0xbfb8aa3b, v93
	v_exp_f32_e32 v101, v101
	v_lshl_add_u64 v[96:97], v[150:151], 0, v[96:97]
	v_add_f32_e32 v100, 1.0, v100
	v_rcp_f32_e32 v104, v100
	v_add_f32_e32 v101, 1.0, v101
	v_rcp_f32_e32 v105, v101
	v_mul_f32_e32 v100, 0x3fb8aa3b, v92
	v_mul_f32_e32 v101, 0x3fb8aa3b, v93
	v_exp_f32_e32 v100, v100
	v_exp_f32_e32 v101, v101
	v_add_f32_e32 v100, 1.0, v100
	v_add_f32_e32 v101, 1.0, v101
	v_rcp_f32_e32 v100, v100
	v_rcp_f32_e32 v101, v101
	s_waitcnt vmcnt(1)
	v_pk_add_f32 v[114:115], v[80:81], 1.0 op_sel_hi:[1,0] neg_lo:[1,0] neg_hi:[1,0]
	s_waitcnt vmcnt(0)
	v_pk_add_f32 v[102:103], v[84:85], 1.0 op_sel_hi:[1,0] neg_lo:[1,0] neg_hi:[1,0]
	v_pk_add_f32 v[106:107], v[86:87], 1.0 op_sel_hi:[1,0] neg_lo:[1,0] neg_hi:[1,0]
	v_fma_f32 v84, v104, v102, v84
	v_max_f32_e32 v84, 0xda24260, v84
	v_fma_f32 v85, v105, v103, v85
	v_max_f32_e32 v85, 0xda24260, v85
	v_log_f32_e32 v84, v84
	v_mul_f32_e32 v105, 0xbfb8aa3b, v95
	v_exp_f32_e32 v105, v105
	v_pk_add_f32 v[116:117], v[82:83], 1.0 op_sel_hi:[1,0] neg_lo:[1,0] neg_hi:[1,0]
	v_mul_f32_e32 v104, 0x3f317217, v84
	v_fma_f32 v104, v84, s95, -v104
	v_fmac_f32_e32 v104, 0x3377d1cf, v84
	v_fmac_f32_e32 v104, 0x3f317217, v84
	v_cmp_lt_f32_e64 s[46:47], |v84|, s62
	v_add_f32_e32 v105, 1.0, v105
	v_rcp_f32_e32 v109, v105
	v_cndmask_b32_e64 v84, v84, v104, s[46:47]
	v_fmac_f32_e32 v87, v109, v107
	v_log_f32_e32 v85, v85
	v_max_f32_e32 v87, 0xda24260, v87
	v_mul_f32_e32 v109, 0xbfb8aa3b, v91
	v_exp_f32_e32 v109, v109
	v_mul_f32_e32 v104, 0x3f317217, v85
	v_fma_f32 v104, v85, s95, -v104
	v_fmac_f32_e32 v104, 0x3377d1cf, v85
	v_fmac_f32_e32 v104, 0x3f317217, v85
	v_cmp_lt_f32_e64 s[46:47], |v85|, s62
	v_add_f32_e32 v109, 1.0, v109
	v_rcp_f32_e32 v111, v109
	v_cndmask_b32_e64 v85, v85, v104, s[46:47]
	v_mul_f32_e32 v104, 0xbfb8aa3b, v94
	v_exp_f32_e32 v104, v104
	v_mul_f32_e32 v105, 0x3fb8aa3b, v95
	v_mul_f32_e32 v109, 0x3fb8aa3b, v91
	v_exp_f32_e32 v105, v105
	v_add_f32_e32 v104, 1.0, v104
	v_rcp_f32_e32 v108, v104
	v_mul_f32_e32 v104, 0x3fb8aa3b, v94
	v_exp_f32_e32 v104, v104
	v_exp_f32_e32 v109, v109
	v_fma_f32 v86, v108, v106, v86
	v_max_f32_e32 v86, 0xda24260, v86
	v_add_f32_e32 v104, 1.0, v104
	v_add_f32_e32 v105, 1.0, v105
	v_log_f32_e32 v86, v86
	v_add_f32_e32 v109, 1.0, v109
	v_rcp_f32_e32 v104, v104
	v_rcp_f32_e32 v105, v105
	v_mul_f32_e32 v108, 0x3f317217, v86
	v_fma_f32 v108, v86, s95, -v108
	v_fmac_f32_e32 v108, 0x3377d1cf, v86
	v_fmac_f32_e32 v108, 0x3f317217, v86
	v_cmp_lt_f32_e64 s[46:47], |v86|, s62
	v_rcp_f32_e32 v109, v109
	v_pk_mul_f32 v[102:103], v[100:101], v[102:103]
	v_cndmask_b32_e64 v86, v86, v108, s[46:47]
	v_pk_mul_f32 v[100:101], v[104:105], v[106:107]
	v_log_f32_e32 v87, v87
	s_nop 0
	v_mul_f32_e32 v108, 0x3f317217, v87
	v_fma_f32 v108, v87, s95, -v108
	v_fmac_f32_e32 v108, 0x3377d1cf, v87
	v_fmac_f32_e32 v108, 0x3f317217, v87
	v_cmp_lt_f32_e64 s[46:47], |v87|, s62
	s_nop 1
	v_cndmask_b32_e64 v87, v87, v108, s[46:47]
	v_mul_f32_e32 v108, 0xbfb8aa3b, v90
	v_exp_f32_e32 v108, v108
	s_nop 0
	v_add_f32_e32 v108, 1.0, v108
	v_rcp_f32_e32 v110, v108
	v_mul_f32_e32 v108, 0x3fb8aa3b, v90
	v_exp_f32_e32 v108, v108
	v_fma_f32 v80, v110, v114, v80
	v_max_f32_e32 v80, 0xda24260, v80
	v_add_f32_e32 v108, 1.0, v108
	v_rcp_f32_e32 v108, v108
	v_log_f32_e32 v80, v80
	s_nop 0
	v_mul_f32_e32 v110, 0x3f317217, v80
	v_fma_f32 v110, v80, s95, -v110
	v_fmac_f32_e32 v110, 0x3377d1cf, v80
	v_fmac_f32_e32 v110, 0x3f317217, v80
	v_cmp_lt_f32_e64 s[46:47], |v80|, s62
	s_nop 1
	v_cndmask_b32_e64 v80, v80, v110, s[46:47]
	v_mov_b32_e32 v110, v80
	v_fma_f32 v80, v111, v115, v81
	v_max_f32_e32 v80, 0xda24260, v80
	s_nop 1
	v_log_f32_e32 v80, v80
	s_nop 0
	v_mul_f32_e32 v81, 0x3f317217, v80
	v_fma_f32 v81, v80, s95, -v81
	v_fmac_f32_e32 v81, 0x3377d1cf, v80
	v_fmac_f32_e32 v81, 0x3f317217, v80
	v_cmp_lt_f32_e64 s[46:47], |v80|, s62
	s_nop 1
	v_cndmask_b32_e64 v80, v80, v81, s[46:47]
	v_mov_b32_e32 v111, v80
	v_mul_f32_e32 v80, 0xbfb8aa3b, v98
	v_exp_f32_e32 v80, v80
	v_mul_f32_e32 v81, 0xbfb8aa3b, v99
	v_exp_f32_e32 v81, v81
	v_add_f32_e32 v80, 1.0, v80
	v_rcp_f32_e32 v112, v80
	v_add_f32_e32 v81, 1.0, v81
	v_rcp_f32_e32 v113, v81
	v_mul_f32_e32 v80, 0x3fb8aa3b, v98
	v_fma_f32 v82, v112, v116, v82
	v_max_f32_e32 v82, 0xda24260, v82
	v_fmac_f32_e32 v83, v113, v117
	v_mul_f32_e32 v81, 0x3fb8aa3b, v99
	v_log_f32_e32 v82, v82
	v_exp_f32_e32 v80, v80
	v_exp_f32_e32 v81, v81
	v_mul_f32_e32 v112, 0x3f317217, v82
	v_fma_f32 v112, v82, s95, -v112
	v_fmac_f32_e32 v112, 0x3377d1cf, v82
	v_fmac_f32_e32 v112, 0x3f317217, v82
	v_cmp_lt_f32_e64 s[46:47], |v82|, s62
	v_add_f32_e32 v80, 1.0, v80
	v_add_f32_e32 v81, 1.0, v81
	v_cndmask_b32_e64 v82, v82, v112, s[46:47]
	v_mov_b32_e32 v112, v82
	v_max_f32_e32 v82, 0xda24260, v83
	v_rcp_f32_e32 v80, v80
	v_rcp_f32_e32 v81, v81
	v_log_f32_e32 v82, v82
	v_pk_mul_f32 v[80:81], v[80:81], v[116:117]
	v_mul_f32_e32 v83, 0x3f317217, v82
	v_fma_f32 v83, v82, s95, -v83
	v_fmac_f32_e32 v83, 0x3377d1cf, v82
	v_fmac_f32_e32 v83, 0x3f317217, v82
	v_cmp_lt_f32_e64 s[46:47], |v82|, s62
	s_nop 1
	v_cndmask_b32_e64 v82, v82, v83, s[46:47]
	v_mov_b32_e32 v113, v82
	v_pk_mul_f32 v[82:83], v[108:109], v[114:115]
	global_store_dwordx4 v[96:97], v[84:87], off
	global_store_dwordx4 v[96:97], v[110:113], off offset:16

.LBB0_432:
	s_andn2_b64 vcc, exec, s[36:37]
	s_cbranch_vccnz .LBB0_434
	v_mul_f32_e32 v80, 0xbfb8aa3b, v94
	v_exp_f32_e32 v80, v80
	v_mul_f32_e32 v105, 0xbfb8aa3b, v97
	v_exp_f32_e32 v105, v105
	v_mul_f32_e32 v109, 0xbfb8aa3b, v93
	v_add_f32_e32 v80, 1.0, v80
	v_rcp_f32_e32 v91, v80
	v_mul_f32_e32 v80, 0x3fb8aa3b, v94
	v_exp_f32_e32 v80, v80
	v_add_f32_e32 v105, 1.0, v105
	v_rcp_f32_e32 v108, v105
	v_exp_f32_e32 v109, v109
	v_add_f32_e32 v80, 1.0, v80
	v_rcp_f32_e32 v100, v80
	v_mul_f32_e32 v80, 0xbfb8aa3b, v95
	v_exp_f32_e32 v80, v80
	v_add_f32_e32 v109, 1.0, v109
	v_rcp_f32_e32 v111, v109
	v_mul_f32_e32 v105, 0x3fb8aa3b, v97
	v_add_f32_e32 v80, 1.0, v80
	v_rcp_f32_e32 v104, v80
	v_mul_f32_e32 v80, 0x3fb8aa3b, v95
	v_exp_f32_e32 v80, v80
	v_mul_f32_e32 v109, 0x3fb8aa3b, v93
	v_exp_f32_e32 v105, v105
	v_exp_f32_e32 v109, v109
	v_add_f32_e32 v80, 1.0, v80
	v_rcp_f32_e32 v101, v80
	global_load_dwordx4 v[80:83], v[148:149], off offset:16
	global_load_dwordx4 v[84:87], v[148:149], off
	v_add_f32_e32 v105, 1.0, v105
	v_add_f32_e32 v109, 1.0, v109
	v_rcp_f32_e32 v105, v105
	v_rcp_f32_e32 v109, v109
	s_waitcnt vmcnt(1)
	v_pk_add_f32 v[114:115], v[80:81], 1.0 op_sel_hi:[1,0] neg_lo:[1,0] neg_hi:[1,0]
	s_waitcnt vmcnt(0)
	v_pk_add_f32 v[102:103], v[84:85], 1.0 op_sel_hi:[1,0] neg_lo:[1,0] neg_hi:[1,0]
	v_pk_add_f32 v[106:107], v[86:87], 1.0 op_sel_hi:[1,0] neg_lo:[1,0] neg_hi:[1,0]
	v_fma_f32 v84, v91, v102, v84
	v_max_f32_e32 v84, 0xda24260, v84
	v_fma_f32 v85, v104, v103, v85
	v_max_f32_e32 v85, 0xda24260, v85
	v_log_f32_e32 v84, v84
	v_fmac_f32_e32 v87, v108, v107
	v_max_f32_e32 v87, 0xda24260, v87
	v_pk_add_f32 v[116:117], v[82:83], 1.0 op_sel_hi:[1,0] neg_lo:[1,0] neg_hi:[1,0]
	v_mul_f32_e32 v91, 0x3f317217, v84
	v_fma_f32 v91, v84, s95, -v91
	v_fmac_f32_e32 v91, 0x3377d1cf, v84
	v_fmac_f32_e32 v91, 0x3f317217, v84
	v_cmp_lt_f32_e64 s[46:47], |v84|, s62
	v_mul_f32_e32 v104, 0x3fb8aa3b, v96
	v_mul_f32_e32 v108, 0x3fb8aa3b, v92
	v_cndmask_b32_e64 v84, v84, v91, s[46:47]
	v_exp_f32_e32 v104, v104
	v_log_f32_e32 v85, v85
	v_exp_f32_e32 v108, v108
	v_add_f32_e32 v104, 1.0, v104
	v_rcp_f32_e32 v104, v104
	v_mul_f32_e32 v91, 0x3f317217, v85
	v_fma_f32 v91, v85, s95, -v91
	v_fmac_f32_e32 v91, 0x3377d1cf, v85
	v_fmac_f32_e32 v91, 0x3f317217, v85
	v_cmp_lt_f32_e64 s[46:47], |v85|, s62
	v_add_f32_e32 v108, 1.0, v108
	v_rcp_f32_e32 v108, v108
	v_cndmask_b32_e64 v85, v85, v91, s[46:47]
	v_mul_f32_e32 v91, 0xbfb8aa3b, v96
	v_exp_f32_e32 v91, v91
	v_pk_mul_f32 v[102:103], v[100:101], v[102:103]
	v_pk_mul_f32 v[100:101], v[104:105], v[106:107]
	v_lshl_add_u64 v[104:105], v[146:147], 0, v[88:89]
	v_add_f32_e32 v91, 1.0, v91
	v_rcp_f32_e32 v91, v91
	s_nop 0
	v_fma_f32 v86, v91, v106, v86
	v_max_f32_e32 v86, 0xda24260, v86
	s_nop 1
	v_log_f32_e32 v86, v86
	s_nop 0
	v_mul_f32_e32 v91, 0x3f317217, v86
	v_fma_f32 v91, v86, s95, -v91
	v_fmac_f32_e32 v91, 0x3377d1cf, v86
	v_fmac_f32_e32 v91, 0x3f317217, v86
	v_cmp_lt_f32_e64 s[46:47], |v86|, s62
	s_nop 1
	v_cndmask_b32_e64 v86, v86, v91, s[46:47]
	s_nop 0
	v_log_f32_e32 v87, v87
	s_nop 0
	v_mul_f32_e32 v91, 0x3f317217, v87
	v_fma_f32 v91, v87, s95, -v91
	v_fmac_f32_e32 v91, 0x3377d1cf, v87
	v_fmac_f32_e32 v91, 0x3f317217, v87
	v_cmp_lt_f32_e64 s[46:47], |v87|, s62
	s_nop 1
	v_cndmask_b32_e64 v87, v87, v91, s[46:47]
	v_mul_f32_e32 v91, 0xbfb8aa3b, v92
	v_exp_f32_e32 v91, v91
	s_nop 0
	v_add_f32_e32 v91, 1.0, v91
	v_rcp_f32_e32 v91, v91
	s_nop 0
	v_fma_f32 v80, v91, v114, v80
	v_max_f32_e32 v80, 0xda24260, v80
	s_nop 1
	v_log_f32_e32 v80, v80
	s_nop 0
	v_mul_f32_e32 v91, 0x3f317217, v80
	v_fma_f32 v91, v80, s95, -v91
	v_fmac_f32_e32 v91, 0x3377d1cf, v80
	v_fmac_f32_e32 v91, 0x3f317217, v80
	v_cmp_lt_f32_e64 s[46:47], |v80|, s62
	s_nop 1
	v_cndmask_b32_e64 v80, v80, v91, s[46:47]
	v_mov_b32_e32 v110, v80
	v_fma_f32 v80, v111, v115, v81
	v_max_f32_e32 v80, 0xda24260, v80
	s_nop 1
	v_log_f32_e32 v80, v80
	s_nop 0
	v_mul_f32_e32 v81, 0x3f317217, v80
	v_fma_f32 v81, v80, s95, -v81
	v_fmac_f32_e32 v81, 0x3377d1cf, v80
	v_fmac_f32_e32 v81, 0x3f317217, v80
	v_cmp_lt_f32_e64 s[46:47], |v80|, s62
	s_nop 1
	v_cndmask_b32_e64 v80, v80, v81, s[46:47]
	v_mov_b32_e32 v111, v80
	v_mul_f32_e32 v80, 0xbfb8aa3b, v98
	v_exp_f32_e32 v80, v80
	v_mul_f32_e32 v81, 0xbfb8aa3b, v99
	v_exp_f32_e32 v81, v81
	v_add_f32_e32 v80, 1.0, v80
	v_rcp_f32_e32 v91, v80
	v_add_f32_e32 v81, 1.0, v81
	v_rcp_f32_e32 v113, v81
	v_mul_f32_e32 v80, 0x3fb8aa3b, v98
	v_fma_f32 v82, v91, v116, v82
	v_max_f32_e32 v82, 0xda24260, v82
	v_fmac_f32_e32 v83, v113, v117
	v_mul_f32_e32 v81, 0x3fb8aa3b, v99
	v_log_f32_e32 v82, v82
	v_exp_f32_e32 v80, v80
	v_exp_f32_e32 v81, v81
	v_mul_f32_e32 v91, 0x3f317217, v82
	v_fma_f32 v91, v82, s95, -v91
	v_fmac_f32_e32 v91, 0x3377d1cf, v82
	v_fmac_f32_e32 v91, 0x3f317217, v82
	v_cmp_lt_f32_e64 s[46:47], |v82|, s62
	v_add_f32_e32 v80, 1.0, v80
	v_add_f32_e32 v81, 1.0, v81
	v_cndmask_b32_e64 v82, v82, v91, s[46:47]
	v_mov_b32_e32 v112, v82
	v_max_f32_e32 v82, 0xda24260, v83
	v_rcp_f32_e32 v80, v80
	v_rcp_f32_e32 v81, v81
	v_log_f32_e32 v82, v82
	v_pk_mul_f32 v[80:81], v[80:81], v[116:117]
	v_mul_f32_e32 v83, 0x3f317217, v82
	v_fma_f32 v83, v82, s95, -v83
	v_fmac_f32_e32 v83, 0x3377d1cf, v82
	v_fmac_f32_e32 v83, 0x3f317217, v82
	v_cmp_lt_f32_e64 s[46:47], |v82|, s62
	s_nop 1
	v_cndmask_b32_e64 v82, v82, v83, s[46:47]
	v_mov_b32_e32 v113, v82
	v_pk_mul_f32 v[82:83], v[108:109], v[114:115]
	global_store_dwordx4 v[104:105], v[84:87], off
	global_store_dwordx4 v[104:105], v[110:113], off offset:16

.LBB0_444:
	s_andn2_b64 vcc, exec, s[36:37]
	s_cbranch_vccnz .LBB0_446
	global_load_dwordx4 v[72:75], v[148:149], off offset:528
	global_load_dwordx4 v[76:79], v[148:149], off offset:512
	v_mul_f32_e32 v92, 0xbfb8aa3b, v84
	v_exp_f32_e32 v92, v92
	v_mul_f32_e32 v93, 0xbfb8aa3b, v85
	v_exp_f32_e32 v93, v93
	v_lshl_add_u64 v[88:89], v[150:151], 0, v[88:89]
	v_add_f32_e32 v92, 1.0, v92
	v_rcp_f32_e32 v96, v92
	v_add_f32_e32 v93, 1.0, v93
	v_rcp_f32_e32 v97, v93
	v_mul_f32_e32 v92, 0x3fb8aa3b, v84
	v_mul_f32_e32 v93, 0x3fb8aa3b, v85
	v_exp_f32_e32 v92, v92
	v_exp_f32_e32 v93, v93
	v_add_f32_e32 v92, 1.0, v92
	v_add_f32_e32 v93, 1.0, v93
	v_rcp_f32_e32 v92, v92
	v_rcp_f32_e32 v93, v93
	s_waitcnt vmcnt(1)
	v_pk_add_f32 v[106:107], v[72:73], 1.0 op_sel_hi:[1,0] neg_lo:[1,0] neg_hi:[1,0]
	s_waitcnt vmcnt(0)
	v_pk_add_f32 v[94:95], v[76:77], 1.0 op_sel_hi:[1,0] neg_lo:[1,0] neg_hi:[1,0]
	v_pk_add_f32 v[98:99], v[78:79], 1.0 op_sel_hi:[1,0] neg_lo:[1,0] neg_hi:[1,0]
	v_fma_f32 v76, v96, v94, v76
	v_max_f32_e32 v76, 0xda24260, v76
	v_fma_f32 v77, v97, v95, v77
	v_max_f32_e32 v77, 0xda24260, v77
	v_log_f32_e32 v76, v76
	v_mul_f32_e32 v97, 0xbfb8aa3b, v87
	v_exp_f32_e32 v97, v97
	v_pk_add_f32 v[108:109], v[74:75], 1.0 op_sel_hi:[1,0] neg_lo:[1,0] neg_hi:[1,0]
	v_mul_f32_e32 v96, 0x3f317217, v76
	v_fma_f32 v96, v76, s95, -v96
	v_fmac_f32_e32 v96, 0x3377d1cf, v76
	v_fmac_f32_e32 v96, 0x3f317217, v76
	v_cmp_lt_f32_e64 s[46:47], |v76|, s62
	v_add_f32_e32 v97, 1.0, v97
	v_rcp_f32_e32 v101, v97
	v_cndmask_b32_e64 v76, v76, v96, s[46:47]
	v_fmac_f32_e32 v79, v101, v99
	v_log_f32_e32 v77, v77
	v_max_f32_e32 v79, 0xda24260, v79
	v_mul_f32_e32 v101, 0xbfb8aa3b, v83
	v_exp_f32_e32 v101, v101
	v_mul_f32_e32 v96, 0x3f317217, v77
	v_fma_f32 v96, v77, s95, -v96
	v_fmac_f32_e32 v96, 0x3377d1cf, v77
	v_fmac_f32_e32 v96, 0x3f317217, v77
	v_cmp_lt_f32_e64 s[46:47], |v77|, s62
	v_add_f32_e32 v101, 1.0, v101
	v_rcp_f32_e32 v103, v101
	v_cndmask_b32_e64 v77, v77, v96, s[46:47]
	v_mul_f32_e32 v96, 0xbfb8aa3b, v86
	v_exp_f32_e32 v96, v96
	v_mul_f32_e32 v97, 0x3fb8aa3b, v87
	v_mul_f32_e32 v101, 0x3fb8aa3b, v83
	v_exp_f32_e32 v97, v97
	v_add_f32_e32 v96, 1.0, v96
	v_rcp_f32_e32 v100, v96
	v_mul_f32_e32 v96, 0x3fb8aa3b, v86
	v_exp_f32_e32 v96, v96
	v_exp_f32_e32 v101, v101
	v_fma_f32 v78, v100, v98, v78
	v_max_f32_e32 v78, 0xda24260, v78
	v_add_f32_e32 v96, 1.0, v96
	v_add_f32_e32 v97, 1.0, v97
	v_log_f32_e32 v78, v78
	v_add_f32_e32 v101, 1.0, v101
	v_rcp_f32_e32 v96, v96
	v_rcp_f32_e32 v97, v97
	v_mul_f32_e32 v100, 0x3f317217, v78
	v_fma_f32 v100, v78, s95, -v100
	v_fmac_f32_e32 v100, 0x3377d1cf, v78
	v_fmac_f32_e32 v100, 0x3f317217, v78
	v_cmp_lt_f32_e64 s[46:47], |v78|, s62
	v_rcp_f32_e32 v101, v101
	v_pk_mul_f32 v[94:95], v[92:93], v[94:95]
	v_cndmask_b32_e64 v78, v78, v100, s[46:47]
	v_pk_mul_f32 v[92:93], v[96:97], v[98:99]
	v_log_f32_e32 v79, v79
	s_nop 0
	v_mul_f32_e32 v100, 0x3f317217, v79
	v_fma_f32 v100, v79, s95, -v100
	v_fmac_f32_e32 v100, 0x3377d1cf, v79
	v_fmac_f32_e32 v100, 0x3f317217, v79
	v_cmp_lt_f32_e64 s[46:47], |v79|, s62
	s_nop 1
	v_cndmask_b32_e64 v79, v79, v100, s[46:47]
	v_mul_f32_e32 v100, 0xbfb8aa3b, v82
	v_exp_f32_e32 v100, v100
	s_nop 0
	v_add_f32_e32 v100, 1.0, v100
	v_rcp_f32_e32 v102, v100
	v_mul_f32_e32 v100, 0x3fb8aa3b, v82
	v_exp_f32_e32 v100, v100
	v_fma_f32 v72, v102, v106, v72
	v_max_f32_e32 v72, 0xda24260, v72
	v_add_f32_e32 v100, 1.0, v100
	v_rcp_f32_e32 v100, v100
	v_log_f32_e32 v72, v72
	s_nop 0
	v_mul_f32_e32 v102, 0x3f317217, v72
	v_fma_f32 v102, v72, s95, -v102
	v_fmac_f32_e32 v102, 0x3377d1cf, v72
	v_fmac_f32_e32 v102, 0x3f317217, v72
	v_cmp_lt_f32_e64 s[46:47], |v72|, s62
	s_nop 1
	v_cndmask_b32_e64 v72, v72, v102, s[46:47]
	v_mov_b32_e32 v102, v72
	v_fma_f32 v72, v103, v107, v73
	v_max_f32_e32 v72, 0xda24260, v72
	s_nop 1
	v_log_f32_e32 v72, v72
	s_nop 0
	v_mul_f32_e32 v73, 0x3f317217, v72
	v_fma_f32 v73, v72, s95, -v73
	v_fmac_f32_e32 v73, 0x3377d1cf, v72
	v_fmac_f32_e32 v73, 0x3f317217, v72
	v_cmp_lt_f32_e64 s[46:47], |v72|, s62
	s_nop 1
	v_cndmask_b32_e64 v72, v72, v73, s[46:47]
	v_mov_b32_e32 v103, v72
	v_mul_f32_e32 v72, 0xbfb8aa3b, v90
	v_exp_f32_e32 v72, v72
	v_mul_f32_e32 v73, 0xbfb8aa3b, v91
	v_exp_f32_e32 v73, v73
	v_add_f32_e32 v72, 1.0, v72
	v_rcp_f32_e32 v104, v72
	v_add_f32_e32 v73, 1.0, v73
	v_rcp_f32_e32 v105, v73
	v_mul_f32_e32 v72, 0x3fb8aa3b, v90
	v_fma_f32 v74, v104, v108, v74
	v_max_f32_e32 v74, 0xda24260, v74
	v_fmac_f32_e32 v75, v105, v109
	v_mul_f32_e32 v73, 0x3fb8aa3b, v91
	v_log_f32_e32 v74, v74
	v_exp_f32_e32 v72, v72
	v_exp_f32_e32 v73, v73
	v_mul_f32_e32 v104, 0x3f317217, v74
	v_fma_f32 v104, v74, s95, -v104
	v_fmac_f32_e32 v104, 0x3377d1cf, v74
	v_fmac_f32_e32 v104, 0x3f317217, v74
	v_cmp_lt_f32_e64 s[46:47], |v74|, s62
	v_add_f32_e32 v72, 1.0, v72
	v_add_f32_e32 v73, 1.0, v73
	v_cndmask_b32_e64 v74, v74, v104, s[46:47]
	v_mov_b32_e32 v104, v74
	v_max_f32_e32 v74, 0xda24260, v75
	v_rcp_f32_e32 v72, v72
	v_rcp_f32_e32 v73, v73
	v_log_f32_e32 v74, v74
	v_pk_mul_f32 v[72:73], v[72:73], v[108:109]
	v_mul_f32_e32 v75, 0x3f317217, v74
	v_fma_f32 v75, v74, s95, -v75
	v_fmac_f32_e32 v75, 0x3377d1cf, v74
	v_fmac_f32_e32 v75, 0x3f317217, v74
	v_cmp_lt_f32_e64 s[46:47], |v74|, s62
	s_nop 1
	v_cndmask_b32_e64 v74, v74, v75, s[46:47]
	v_mov_b32_e32 v105, v74
	v_pk_mul_f32 v[74:75], v[100:101], v[106:107]
	global_store_dwordx4 v[88:89], v[76:79], off
	global_store_dwordx4 v[88:89], v[102:105], off offset:16

.LBB0_456:
	s_andn2_b64 vcc, exec, s[36:37]
	s_cbranch_vccnz .LBB0_458
	v_mul_f32_e32 v72, 0xbfb8aa3b, v86
	v_exp_f32_e32 v72, v72
	v_mul_f32_e32 v97, 0xbfb8aa3b, v89
	v_exp_f32_e32 v97, v97
	v_mul_f32_e32 v101, 0xbfb8aa3b, v85
	v_add_f32_e32 v72, 1.0, v72
	v_rcp_f32_e32 v83, v72
	v_mul_f32_e32 v72, 0x3fb8aa3b, v86
	v_exp_f32_e32 v72, v72
	v_add_f32_e32 v97, 1.0, v97
	v_rcp_f32_e32 v100, v97
	v_exp_f32_e32 v101, v101
	v_add_f32_e32 v72, 1.0, v72
	v_rcp_f32_e32 v92, v72
	v_mul_f32_e32 v72, 0xbfb8aa3b, v87
	v_exp_f32_e32 v72, v72
	v_add_f32_e32 v101, 1.0, v101
	v_rcp_f32_e32 v103, v101
	v_mul_f32_e32 v97, 0x3fb8aa3b, v89
	v_add_f32_e32 v72, 1.0, v72
	v_rcp_f32_e32 v96, v72
	v_mul_f32_e32 v72, 0x3fb8aa3b, v87
	v_exp_f32_e32 v72, v72
	v_mul_f32_e32 v101, 0x3fb8aa3b, v85
	v_exp_f32_e32 v97, v97
	v_exp_f32_e32 v101, v101
	v_add_f32_e32 v72, 1.0, v72
	v_rcp_f32_e32 v93, v72
	global_load_dwordx4 v[72:75], v[148:149], off offset:16
	global_load_dwordx4 v[76:79], v[148:149], off
	v_add_f32_e32 v97, 1.0, v97
	v_add_f32_e32 v101, 1.0, v101
	v_rcp_f32_e32 v97, v97
	v_rcp_f32_e32 v101, v101
	s_waitcnt vmcnt(1)
	v_pk_add_f32 v[106:107], v[72:73], 1.0 op_sel_hi:[1,0] neg_lo:[1,0] neg_hi:[1,0]
	s_waitcnt vmcnt(0)
	v_pk_add_f32 v[94:95], v[76:77], 1.0 op_sel_hi:[1,0] neg_lo:[1,0] neg_hi:[1,0]
	v_pk_add_f32 v[98:99], v[78:79], 1.0 op_sel_hi:[1,0] neg_lo:[1,0] neg_hi:[1,0]
	v_fma_f32 v76, v83, v94, v76
	v_max_f32_e32 v76, 0xda24260, v76
	v_fma_f32 v77, v96, v95, v77
	v_max_f32_e32 v77, 0xda24260, v77
	v_log_f32_e32 v76, v76
	v_fmac_f32_e32 v79, v100, v99
	v_max_f32_e32 v79, 0xda24260, v79
	v_pk_add_f32 v[108:109], v[74:75], 1.0 op_sel_hi:[1,0] neg_lo:[1,0] neg_hi:[1,0]
	v_mul_f32_e32 v83, 0x3f317217, v76
	v_fma_f32 v83, v76, s95, -v83
	v_fmac_f32_e32 v83, 0x3377d1cf, v76
	v_fmac_f32_e32 v83, 0x3f317217, v76
	v_cmp_lt_f32_e64 s[46:47], |v76|, s62
	v_mul_f32_e32 v96, 0x3fb8aa3b, v88
	v_mul_f32_e32 v100, 0x3fb8aa3b, v84
	v_cndmask_b32_e64 v76, v76, v83, s[46:47]
	v_exp_f32_e32 v96, v96
	v_log_f32_e32 v77, v77
	v_exp_f32_e32 v100, v100
	v_add_f32_e32 v96, 1.0, v96
	v_rcp_f32_e32 v96, v96
	v_mul_f32_e32 v83, 0x3f317217, v77
	v_fma_f32 v83, v77, s95, -v83
	v_fmac_f32_e32 v83, 0x3377d1cf, v77
	v_fmac_f32_e32 v83, 0x3f317217, v77
	v_cmp_lt_f32_e64 s[46:47], |v77|, s62
	v_add_f32_e32 v100, 1.0, v100
	v_rcp_f32_e32 v100, v100
	v_cndmask_b32_e64 v77, v77, v83, s[46:47]
	v_mul_f32_e32 v83, 0xbfb8aa3b, v88
	v_exp_f32_e32 v83, v83
	v_pk_mul_f32 v[94:95], v[92:93], v[94:95]
	v_pk_mul_f32 v[92:93], v[96:97], v[98:99]
	v_lshl_add_u64 v[96:97], v[146:147], 0, v[80:81]
	v_add_f32_e32 v83, 1.0, v83
	v_rcp_f32_e32 v83, v83
	s_nop 0
	v_fma_f32 v78, v83, v98, v78
	v_max_f32_e32 v78, 0xda24260, v78
	s_nop 1
	v_log_f32_e32 v78, v78
	s_nop 0
	v_mul_f32_e32 v83, 0x3f317217, v78
	v_fma_f32 v83, v78, s95, -v83
	v_fmac_f32_e32 v83, 0x3377d1cf, v78
	v_fmac_f32_e32 v83, 0x3f317217, v78
	v_cmp_lt_f32_e64 s[46:47], |v78|, s62
	s_nop 1
	v_cndmask_b32_e64 v78, v78, v83, s[46:47]
	s_nop 0
	v_log_f32_e32 v79, v79
	s_nop 0
	v_mul_f32_e32 v83, 0x3f317217, v79
	v_fma_f32 v83, v79, s95, -v83
	v_fmac_f32_e32 v83, 0x3377d1cf, v79
	v_fmac_f32_e32 v83, 0x3f317217, v79
	v_cmp_lt_f32_e64 s[46:47], |v79|, s62
	s_nop 1
	v_cndmask_b32_e64 v79, v79, v83, s[46:47]
	v_mul_f32_e32 v83, 0xbfb8aa3b, v84
	v_exp_f32_e32 v83, v83
	s_nop 0
	v_add_f32_e32 v83, 1.0, v83
	v_rcp_f32_e32 v83, v83
	s_nop 0
	v_fma_f32 v72, v83, v106, v72
	v_max_f32_e32 v72, 0xda24260, v72
	s_nop 1
	v_log_f32_e32 v72, v72
	s_nop 0
	v_mul_f32_e32 v83, 0x3f317217, v72
	v_fma_f32 v83, v72, s95, -v83
	v_fmac_f32_e32 v83, 0x3377d1cf, v72
	v_fmac_f32_e32 v83, 0x3f317217, v72
	v_cmp_lt_f32_e64 s[46:47], |v72|, s62
	s_nop 1
	v_cndmask_b32_e64 v72, v72, v83, s[46:47]
	v_mov_b32_e32 v102, v72
	v_fma_f32 v72, v103, v107, v73
	v_max_f32_e32 v72, 0xda24260, v72
	s_nop 1
	v_log_f32_e32 v72, v72
	s_nop 0
	v_mul_f32_e32 v73, 0x3f317217, v72
	v_fma_f32 v73, v72, s95, -v73
	v_fmac_f32_e32 v73, 0x3377d1cf, v72
	v_fmac_f32_e32 v73, 0x3f317217, v72
	v_cmp_lt_f32_e64 s[46:47], |v72|, s62
	s_nop 1
	v_cndmask_b32_e64 v72, v72, v73, s[46:47]
	v_mov_b32_e32 v103, v72
	v_mul_f32_e32 v72, 0xbfb8aa3b, v90
	v_exp_f32_e32 v72, v72
	v_mul_f32_e32 v73, 0xbfb8aa3b, v91
	v_exp_f32_e32 v73, v73
	v_add_f32_e32 v72, 1.0, v72
	v_rcp_f32_e32 v83, v72
	v_add_f32_e32 v73, 1.0, v73
	v_rcp_f32_e32 v105, v73
	v_mul_f32_e32 v72, 0x3fb8aa3b, v90
	v_fma_f32 v74, v83, v108, v74
	v_max_f32_e32 v74, 0xda24260, v74
	v_fmac_f32_e32 v75, v105, v109
	v_mul_f32_e32 v73, 0x3fb8aa3b, v91
	v_log_f32_e32 v74, v74
	v_exp_f32_e32 v72, v72
	v_exp_f32_e32 v73, v73
	v_mul_f32_e32 v83, 0x3f317217, v74
	v_fma_f32 v83, v74, s95, -v83
	v_fmac_f32_e32 v83, 0x3377d1cf, v74
	v_fmac_f32_e32 v83, 0x3f317217, v74
	v_cmp_lt_f32_e64 s[46:47], |v74|, s62
	v_add_f32_e32 v72, 1.0, v72
	v_add_f32_e32 v73, 1.0, v73
	v_cndmask_b32_e64 v74, v74, v83, s[46:47]
	v_mov_b32_e32 v104, v74
	v_max_f32_e32 v74, 0xda24260, v75
	v_rcp_f32_e32 v72, v72
	v_rcp_f32_e32 v73, v73
	v_log_f32_e32 v74, v74
	v_pk_mul_f32 v[72:73], v[72:73], v[108:109]
	v_mul_f32_e32 v75, 0x3f317217, v74
	v_fma_f32 v75, v74, s95, -v75
	v_fmac_f32_e32 v75, 0x3377d1cf, v74
	v_fmac_f32_e32 v75, 0x3f317217, v74
	v_cmp_lt_f32_e64 s[46:47], |v74|, s62
	s_nop 1
	v_cndmask_b32_e64 v74, v74, v75, s[46:47]
	v_mov_b32_e32 v105, v74
	v_pk_mul_f32 v[74:75], v[100:101], v[106:107]
	global_store_dwordx4 v[96:97], v[76:79], off
	global_store_dwordx4 v[96:97], v[102:105], off offset:16

.LBB0_468:
	s_andn2_b64 vcc, exec, s[30:31]
	s_cbranch_vccnz .LBB0_470
	global_load_dwordx4 v[64:67], v[148:149], off offset:528
	global_load_dwordx4 v[68:71], v[148:149], off offset:512
	v_mul_f32_e32 v84, 0xbfb8aa3b, v76
	v_exp_f32_e32 v84, v84
	v_mul_f32_e32 v85, 0xbfb8aa3b, v77
	v_exp_f32_e32 v85, v85
	v_lshl_add_u64 v[80:81], v[150:151], 0, v[80:81]
	v_add_f32_e32 v84, 1.0, v84
	v_rcp_f32_e32 v88, v84
	v_add_f32_e32 v85, 1.0, v85
	v_rcp_f32_e32 v89, v85
	v_mul_f32_e32 v84, 0x3fb8aa3b, v76
	v_mul_f32_e32 v85, 0x3fb8aa3b, v77
	v_exp_f32_e32 v84, v84
	v_exp_f32_e32 v85, v85
	v_add_f32_e32 v84, 1.0, v84
	v_add_f32_e32 v85, 1.0, v85
	v_rcp_f32_e32 v84, v84
	v_rcp_f32_e32 v85, v85
	s_waitcnt vmcnt(1)
	v_pk_add_f32 v[98:99], v[64:65], 1.0 op_sel_hi:[1,0] neg_lo:[1,0] neg_hi:[1,0]
	s_waitcnt vmcnt(0)
	v_pk_add_f32 v[86:87], v[68:69], 1.0 op_sel_hi:[1,0] neg_lo:[1,0] neg_hi:[1,0]
	v_pk_add_f32 v[90:91], v[70:71], 1.0 op_sel_hi:[1,0] neg_lo:[1,0] neg_hi:[1,0]
	v_fma_f32 v68, v88, v86, v68
	v_max_f32_e32 v68, 0xda24260, v68
	v_fma_f32 v69, v89, v87, v69
	v_max_f32_e32 v69, 0xda24260, v69
	v_log_f32_e32 v68, v68
	v_mul_f32_e32 v89, 0xbfb8aa3b, v79
	v_exp_f32_e32 v89, v89
	v_pk_add_f32 v[100:101], v[66:67], 1.0 op_sel_hi:[1,0] neg_lo:[1,0] neg_hi:[1,0]
	v_mul_f32_e32 v88, 0x3f317217, v68
	v_fma_f32 v88, v68, s95, -v88
	v_fmac_f32_e32 v88, 0x3377d1cf, v68
	v_fmac_f32_e32 v88, 0x3f317217, v68
	v_cmp_lt_f32_e64 s[42:43], |v68|, s62
	v_add_f32_e32 v89, 1.0, v89
	v_rcp_f32_e32 v93, v89
	v_cndmask_b32_e64 v68, v68, v88, s[42:43]
	v_fmac_f32_e32 v71, v93, v91
	v_log_f32_e32 v69, v69
	v_max_f32_e32 v71, 0xda24260, v71
	v_mul_f32_e32 v93, 0xbfb8aa3b, v75
	v_exp_f32_e32 v93, v93
	v_mul_f32_e32 v88, 0x3f317217, v69
	v_fma_f32 v88, v69, s95, -v88
	v_fmac_f32_e32 v88, 0x3377d1cf, v69
	v_fmac_f32_e32 v88, 0x3f317217, v69
	v_cmp_lt_f32_e64 s[42:43], |v69|, s62
	v_add_f32_e32 v93, 1.0, v93
	v_rcp_f32_e32 v95, v93
	v_cndmask_b32_e64 v69, v69, v88, s[42:43]
	v_mul_f32_e32 v88, 0xbfb8aa3b, v78
	v_exp_f32_e32 v88, v88
	v_mul_f32_e32 v89, 0x3fb8aa3b, v79
	v_mul_f32_e32 v93, 0x3fb8aa3b, v75
	v_exp_f32_e32 v89, v89
	v_add_f32_e32 v88, 1.0, v88
	v_rcp_f32_e32 v92, v88
	v_mul_f32_e32 v88, 0x3fb8aa3b, v78
	v_exp_f32_e32 v88, v88
	v_exp_f32_e32 v93, v93
	v_fma_f32 v70, v92, v90, v70
	v_max_f32_e32 v70, 0xda24260, v70
	v_add_f32_e32 v88, 1.0, v88
	v_add_f32_e32 v89, 1.0, v89
	v_log_f32_e32 v70, v70
	v_add_f32_e32 v93, 1.0, v93
	v_rcp_f32_e32 v88, v88
	v_rcp_f32_e32 v89, v89
	v_mul_f32_e32 v92, 0x3f317217, v70
	v_fma_f32 v92, v70, s95, -v92
	v_fmac_f32_e32 v92, 0x3377d1cf, v70
	v_fmac_f32_e32 v92, 0x3f317217, v70
	v_cmp_lt_f32_e64 s[42:43], |v70|, s62
	v_rcp_f32_e32 v93, v93
	v_pk_mul_f32 v[86:87], v[84:85], v[86:87]
	v_cndmask_b32_e64 v70, v70, v92, s[42:43]
	v_pk_mul_f32 v[84:85], v[88:89], v[90:91]
	v_log_f32_e32 v71, v71
	s_nop 0
	v_mul_f32_e32 v92, 0x3f317217, v71
	v_fma_f32 v92, v71, s95, -v92
	v_fmac_f32_e32 v92, 0x3377d1cf, v71
	v_fmac_f32_e32 v92, 0x3f317217, v71
	v_cmp_lt_f32_e64 s[42:43], |v71|, s62
	s_nop 1
	v_cndmask_b32_e64 v71, v71, v92, s[42:43]
	v_mul_f32_e32 v92, 0xbfb8aa3b, v74
	v_exp_f32_e32 v92, v92
	s_nop 0
	v_add_f32_e32 v92, 1.0, v92
	v_rcp_f32_e32 v94, v92
	v_mul_f32_e32 v92, 0x3fb8aa3b, v74
	v_exp_f32_e32 v92, v92
	v_fma_f32 v64, v94, v98, v64
	v_max_f32_e32 v64, 0xda24260, v64
	v_add_f32_e32 v92, 1.0, v92
	v_rcp_f32_e32 v92, v92
	v_log_f32_e32 v64, v64
	s_nop 0
	v_mul_f32_e32 v94, 0x3f317217, v64
	v_fma_f32 v94, v64, s95, -v94
	v_fmac_f32_e32 v94, 0x3377d1cf, v64
	v_fmac_f32_e32 v94, 0x3f317217, v64
	v_cmp_lt_f32_e64 s[42:43], |v64|, s62
	s_nop 1
	v_cndmask_b32_e64 v64, v64, v94, s[42:43]
	v_mov_b32_e32 v94, v64
	v_fma_f32 v64, v95, v99, v65
	v_max_f32_e32 v64, 0xda24260, v64
	s_nop 1
	v_log_f32_e32 v64, v64
	s_nop 0
	v_mul_f32_e32 v65, 0x3f317217, v64
	v_fma_f32 v65, v64, s95, -v65
	v_fmac_f32_e32 v65, 0x3377d1cf, v64
	v_fmac_f32_e32 v65, 0x3f317217, v64
	v_cmp_lt_f32_e64 s[42:43], |v64|, s62
	s_nop 1
	v_cndmask_b32_e64 v64, v64, v65, s[42:43]
	v_mov_b32_e32 v95, v64
	v_mul_f32_e32 v64, 0xbfb8aa3b, v82
	v_exp_f32_e32 v64, v64
	v_mul_f32_e32 v65, 0xbfb8aa3b, v83
	v_exp_f32_e32 v65, v65
	v_add_f32_e32 v64, 1.0, v64
	v_rcp_f32_e32 v96, v64
	v_add_f32_e32 v65, 1.0, v65
	v_rcp_f32_e32 v97, v65
	v_mul_f32_e32 v64, 0x3fb8aa3b, v82
	v_fma_f32 v66, v96, v100, v66
	v_max_f32_e32 v66, 0xda24260, v66
	v_fmac_f32_e32 v67, v97, v101
	v_mul_f32_e32 v65, 0x3fb8aa3b, v83
	v_log_f32_e32 v66, v66
	v_exp_f32_e32 v64, v64
	v_exp_f32_e32 v65, v65
	v_mul_f32_e32 v96, 0x3f317217, v66
	v_fma_f32 v96, v66, s95, -v96
	v_fmac_f32_e32 v96, 0x3377d1cf, v66
	v_fmac_f32_e32 v96, 0x3f317217, v66
	v_cmp_lt_f32_e64 s[42:43], |v66|, s62
	v_add_f32_e32 v64, 1.0, v64
	v_add_f32_e32 v65, 1.0, v65
	v_cndmask_b32_e64 v66, v66, v96, s[42:43]
	v_mov_b32_e32 v96, v66
	v_max_f32_e32 v66, 0xda24260, v67
	v_rcp_f32_e32 v64, v64
	v_rcp_f32_e32 v65, v65
	v_log_f32_e32 v66, v66
	v_pk_mul_f32 v[64:65], v[64:65], v[100:101]
	v_mul_f32_e32 v67, 0x3f317217, v66
	v_fma_f32 v67, v66, s95, -v67
	v_fmac_f32_e32 v67, 0x3377d1cf, v66
	v_fmac_f32_e32 v67, 0x3f317217, v66
	v_cmp_lt_f32_e64 s[42:43], |v66|, s62
	s_nop 1
	v_cndmask_b32_e64 v66, v66, v67, s[42:43]
	v_mov_b32_e32 v97, v66
	v_pk_mul_f32 v[66:67], v[92:93], v[98:99]
	global_store_dwordx4 v[80:81], v[68:71], off
	global_store_dwordx4 v[80:81], v[94:97], off offset:16
